# back-edge rotation of the three GEMM K-loops: the loop-closing barrier is the loop head, the back-edge branch is taken before the wave parks; exit path has its own barrier
# speedup vs baseline: 1.0027x; 1.0027x over previous
.LBB0_233:
	v_mov_b64_e32 v[0:1], 0x5a0
	s_ashr_i32 s95, s94, 31
	v_cmp_lt_i64_e32 vcc, s[34:35], v[0:1]
	s_lshl_b64 s[34:35], s[94:95], 20
	s_add_u32 s96, s56, s34
	s_addc_u32 s97, s57, s35
	s_and_b64 s[34:35], vcc, exec
	s_cselect_b32 s9, s97, s11
	s_cselect_b32 s89, s96, s10
	s_ashr_i32 s71, s70, 31
	s_lshl_b64 s[34:35], s[70:71], 20
	s_add_u32 s98, s82, s34
	s_addc_u32 s99, s83, s35
	s_and_b64 s[34:35], vcc, exec
	s_cselect_b32 s71, s99, s29
	s_cselect_b32 s91, s98, s28
	s_add_u32 s10, s10, 0x80080
	s_addc_u32 s11, s11, 0
	s_add_u32 s93, s28, 0x100
	s_addc_u32 s95, s29, 0
	s_mov_b32 vcc_lo, -2
	ds_read_b128 v[136:139], v167
	ds_read_b128 v[140:143], v167 offset:1024
	ds_read_b128 v[144:147], v167 offset:2048
	ds_read_b128 v[148:151], v167 offset:3072
	s_add_u32 s3, s10, 0xfff80080
	s_addc_u32 s28, s11, -1
	s_cmp_eq_u32 vcc_lo, 28
	s_cselect_b32 s35, s9, s28
	s_cselect_b32 s34, s89, s3
	s_cselect_b32 s29, s71, s95
	s_cselect_b32 s28, s91, s93
	v_lshl_add_u64 v[152:153], s[10:11], 0, v[132:133]
	s_add_i32 m0, s62, 0xc000
	ds_read_b128 v[172:175], v168
	ds_read_b128 v[190:193], v168 offset:1024
	ds_read_b128 v[194:197], v168 offset:2048
	ds_read_b128 v[198:201], v168 offset:3072
	ds_read_b128 v[202:205], v168 offset:4096
	ds_read_b128 v[206:209], v168 offset:5120
	ds_read_b128 v[224:227], v168 offset:6144
	ds_read_b128 v[228:231], v168 offset:7168
	global_load_lds_dwordx4 v[152:153], off
	s_add_i32 m0, s62, 0xe000
	v_lshl_add_u64 v[152:153], s[10:11], 0, v[134:135]
	global_load_lds_dwordx4 v[152:153], off
	s_waitcnt lgkmcnt(8)
	s_barrier
	s_waitcnt lgkmcnt(0)
	v_mfma_f32_16x16x32_bf16 v[124:127], v[136:139], v[172:175], 0
	v_mfma_f32_16x16x32_bf16 v[116:119], v[144:147], v[172:175], 0
	v_mfma_f32_16x16x32_bf16 v[108:111], v[136:139], v[194:197], 0
	v_mfma_f32_16x16x32_bf16 v[100:103], v[144:147], v[194:197], 0
	v_mfma_f32_16x16x32_bf16 v[92:95], v[136:139], v[202:205], 0
	v_mfma_f32_16x16x32_bf16 v[84:87], v[144:147], v[202:205], 0
	v_mfma_f32_16x16x32_bf16 v[76:79], v[136:139], v[224:227], 0
	v_mfma_f32_16x16x32_bf16 v[68:71], v[144:147], v[224:227], 0
	v_mfma_f32_16x16x32_bf16 v[124:127], v[140:143], v[190:193], v[124:127]
	v_mfma_f32_16x16x32_bf16 v[116:119], v[148:151], v[190:193], v[116:119]
	v_mfma_f32_16x16x32_bf16 v[108:111], v[140:143], v[198:201], v[108:111]
	v_mfma_f32_16x16x32_bf16 v[100:103], v[148:151], v[198:201], v[100:103]
	v_mfma_f32_16x16x32_bf16 v[92:95], v[140:143], v[206:209], v[92:95]
	v_mfma_f32_16x16x32_bf16 v[84:87], v[148:151], v[206:209], v[84:87]
	v_mfma_f32_16x16x32_bf16 v[76:79], v[140:143], v[228:231], v[76:79]
	v_mfma_f32_16x16x32_bf16 v[68:71], v[148:151], v[228:231], v[68:71]
	s_barrier
	s_add_i32 s3, s84, s61
	v_lshl_add_u64 v[152:153], s[28:29], 0, v[184:185]
	s_mov_b32 m0, s3
	ds_read_b128 v[232:235], v169
	ds_read_b128 v[236:239], v169 offset:1024
	ds_read_b128 v[240:243], v169 offset:2048
	ds_read_b128 v[244:247], v169 offset:3072
	global_load_lds_dwordx4 v[152:153], off
	s_add_i32 m0, s3, 0x2000
	v_lshl_add_u64 v[248:249], s[28:29], 0, v[188:189]
	global_load_lds_dwordx4 v[248:249], off
	s_barrier
	s_waitcnt lgkmcnt(0)
	v_mfma_f32_16x16x32_bf16 v[120:123], v[232:235], v[172:175], 0
	v_mfma_f32_16x16x32_bf16 v[112:115], v[240:243], v[172:175], 0
	v_mfma_f32_16x16x32_bf16 v[104:107], v[232:235], v[194:197], 0
	v_mfma_f32_16x16x32_bf16 v[96:99], v[240:243], v[194:197], 0
	v_mfma_f32_16x16x32_bf16 v[88:91], v[232:235], v[202:205], 0
	v_mfma_f32_16x16x32_bf16 v[80:83], v[240:243], v[202:205], 0
	v_mfma_f32_16x16x32_bf16 v[72:75], v[232:235], v[224:227], 0
	v_mfma_f32_16x16x32_bf16 v[64:67], v[240:243], v[224:227], 0
	v_mfma_f32_16x16x32_bf16 v[120:123], v[236:239], v[190:193], v[120:123]
	v_mfma_f32_16x16x32_bf16 v[112:115], v[244:247], v[190:193], v[112:115]
	v_mfma_f32_16x16x32_bf16 v[104:107], v[236:239], v[198:201], v[104:107]
	v_mfma_f32_16x16x32_bf16 v[96:99], v[244:247], v[198:201], v[96:99]
	v_mfma_f32_16x16x32_bf16 v[88:91], v[236:239], v[206:209], v[88:91]
	v_mfma_f32_16x16x32_bf16 v[80:83], v[244:247], v[206:209], v[80:83]
	v_mfma_f32_16x16x32_bf16 v[72:75], v[236:239], v[228:231], v[72:75]
	v_mfma_f32_16x16x32_bf16 v[64:67], v[244:247], v[228:231], v[64:67]
	s_mov_b32 m0, s62
	v_lshl_add_u64 v[250:251], s[34:35], 0, v[182:183]
	s_barrier
	ds_read_b128 v[172:175], v168 offset:16384
	ds_read_b128 v[190:193], v168 offset:17408
	ds_read_b128 v[194:197], v168 offset:18432
	ds_read_b128 v[198:201], v168 offset:19456
	ds_read_b128 v[202:205], v168 offset:20480
	ds_read_b128 v[206:209], v168 offset:21504
	ds_read_b128 v[224:227], v168 offset:22528
	ds_read_b128 v[228:231], v168 offset:23552
	global_load_lds_dwordx4 v[250:251], off
	s_mov_b32 m0, s63
	v_lshl_add_u64 v[252:253], s[34:35], 0, v[186:187]
	global_load_lds_dwordx4 v[252:253], off
	s_barrier
	s_waitcnt lgkmcnt(0)
	v_mfma_f32_16x16x32_bf16 v[60:63], v[136:139], v[172:175], 0
	v_mfma_f32_16x16x32_bf16 v[52:55], v[144:147], v[172:175], 0
	v_mfma_f32_16x16x32_bf16 v[44:47], v[136:139], v[194:197], 0
	v_mfma_f32_16x16x32_bf16 v[36:39], v[144:147], v[194:197], 0
	v_mfma_f32_16x16x32_bf16 v[28:31], v[136:139], v[202:205], 0
	v_mfma_f32_16x16x32_bf16 v[20:23], v[144:147], v[202:205], 0
	v_mfma_f32_16x16x32_bf16 v[12:15], v[136:139], v[224:227], 0
	v_mfma_f32_16x16x32_bf16 v[4:7], v[144:147], v[224:227], 0
	v_mfma_f32_16x16x32_bf16 v[60:63], v[140:143], v[190:193], v[60:63]
	v_mfma_f32_16x16x32_bf16 v[52:55], v[148:151], v[190:193], v[52:55]
	v_mfma_f32_16x16x32_bf16 v[44:47], v[140:143], v[198:201], v[44:47]
	v_mfma_f32_16x16x32_bf16 v[36:39], v[148:151], v[198:201], v[36:39]
	v_mfma_f32_16x16x32_bf16 v[28:31], v[140:143], v[206:209], v[28:31]
	v_mfma_f32_16x16x32_bf16 v[20:23], v[148:151], v[206:209], v[20:23]
	v_mfma_f32_16x16x32_bf16 v[12:15], v[140:143], v[228:231], v[12:15]
	v_mfma_f32_16x16x32_bf16 v[4:7], v[148:151], v[228:231], v[4:7]
	s_barrier
	s_add_u32 s74, s28, 0x80000
	s_addc_u32 s75, s29, 0
	s_add_i32 s3, s85, s61
	s_mov_b32 m0, s3
	v_lshl_add_u64 v[136:137], s[74:75], 0, v[184:185]
	global_load_lds_dwordx4 v[136:137], off
	s_add_i32 m0, s3, 0x2000
	v_lshl_add_u64 v[136:137], s[74:75], 0, v[188:189]
	global_load_lds_dwordx4 v[136:137], off
	s_waitcnt vmcnt(6)
	s_barrier
	v_mfma_f32_16x16x32_bf16 v[56:59], v[232:235], v[172:175], 0
	v_mfma_f32_16x16x32_bf16 v[48:51], v[240:243], v[172:175], 0
	v_mfma_f32_16x16x32_bf16 v[40:43], v[232:235], v[194:197], 0
	v_mfma_f32_16x16x32_bf16 v[32:35], v[240:243], v[194:197], 0
	v_mfma_f32_16x16x32_bf16 v[24:27], v[232:235], v[202:205], 0
	v_mfma_f32_16x16x32_bf16 v[16:19], v[240:243], v[202:205], 0
	v_mfma_f32_16x16x32_bf16 v[8:11], v[232:235], v[224:227], 0
	v_mfma_f32_16x16x32_bf16 v[0:3], v[240:243], v[224:227], 0
	v_mfma_f32_16x16x32_bf16 v[56:59], v[236:239], v[190:193], v[56:59]
	v_mfma_f32_16x16x32_bf16 v[48:51], v[244:247], v[190:193], v[48:51]
	v_mfma_f32_16x16x32_bf16 v[40:43], v[236:239], v[198:201], v[40:43]
	v_mfma_f32_16x16x32_bf16 v[32:35], v[244:247], v[198:201], v[32:35]
	v_mfma_f32_16x16x32_bf16 v[24:27], v[236:239], v[206:209], v[24:27]
	v_mfma_f32_16x16x32_bf16 v[16:19], v[244:247], v[206:209], v[16:19]
	v_mfma_f32_16x16x32_bf16 v[8:11], v[236:239], v[228:231], v[8:11]
	v_mfma_f32_16x16x32_bf16 v[0:3], v[244:247], v[228:231], v[0:3]
	s_add_i32 s3, 0, 0x18000
	s_barrier
	ds_read_b128 v[136:139], v171
	ds_read_b128 v[140:143], v171 offset:1024
	ds_read_b128 v[144:147], v171 offset:2048
	ds_read_b128 v[148:151], v171 offset:3072
	s_add_u32 s34, s34, 0x80000
	s_addc_u32 s35, s35, 0
	s_mov_b32 m0, s64
	v_lshl_add_u64 v[232:233], s[34:35], 0, v[182:183]
	ds_read_b128 v[172:175], v168 offset:32768
	ds_read_b128 v[190:193], v168 offset:33792
	ds_read_b128 v[194:197], v168 offset:34816
	ds_read_b128 v[198:201], v168 offset:35840
	ds_read_b128 v[202:205], v168 offset:36864
	ds_read_b128 v[206:209], v168 offset:37888
	ds_read_b128 v[224:227], v168 offset:38912
	ds_read_b128 v[228:231], v168 offset:39936
	global_load_lds_dwordx4 v[232:233], off
	s_mov_b32 m0, s65
	v_lshl_add_u64 v[232:233], s[34:35], 0, v[186:187]
	global_load_lds_dwordx4 v[232:233], off
	s_waitcnt lgkmcnt(8)
	s_barrier
	s_waitcnt lgkmcnt(0)
	v_mfma_f32_16x16x32_bf16 v[124:127], v[136:139], v[172:175], v[124:127]
	v_mfma_f32_16x16x32_bf16 v[116:119], v[144:147], v[172:175], v[116:119]
	v_mfma_f32_16x16x32_bf16 v[108:111], v[136:139], v[194:197], v[108:111]
	v_mfma_f32_16x16x32_bf16 v[100:103], v[144:147], v[194:197], v[100:103]
	v_mfma_f32_16x16x32_bf16 v[92:95], v[136:139], v[202:205], v[92:95]
	v_mfma_f32_16x16x32_bf16 v[84:87], v[144:147], v[202:205], v[84:87]
	v_mfma_f32_16x16x32_bf16 v[76:79], v[136:139], v[224:227], v[76:79]
	v_mfma_f32_16x16x32_bf16 v[68:71], v[144:147], v[224:227], v[68:71]
	v_mfma_f32_16x16x32_bf16 v[124:127], v[140:143], v[190:193], v[124:127]
	v_mfma_f32_16x16x32_bf16 v[116:119], v[148:151], v[190:193], v[116:119]
	v_mfma_f32_16x16x32_bf16 v[108:111], v[140:143], v[198:201], v[108:111]
	v_mfma_f32_16x16x32_bf16 v[100:103], v[148:151], v[198:201], v[100:103]
	v_mfma_f32_16x16x32_bf16 v[92:95], v[140:143], v[206:209], v[92:95]
	v_mfma_f32_16x16x32_bf16 v[84:87], v[148:151], v[206:209], v[84:87]
	v_mfma_f32_16x16x32_bf16 v[76:79], v[140:143], v[228:231], v[76:79]
	v_mfma_f32_16x16x32_bf16 v[68:71], v[148:151], v[228:231], v[68:71]
	s_barrier
	s_add_i32 s33, 0, 0x1c000
	s_add_i32 s3, s3, s61
	v_lshl_add_u64 v[152:153], v[152:153], 0, s[86:87]
	s_mov_b32 m0, s3
	ds_read_b128 v[232:235], v255
	ds_read_b128 v[236:239], v255 offset:1024
	ds_read_b128 v[240:243], v255 offset:2048
	ds_read_b128 v[244:247], v255 offset:3072
	global_load_lds_dwordx4 v[152:153], off
	s_add_i32 m0, s3, 0x2000
	v_lshl_add_u64 v[152:153], v[248:249], 0, s[86:87]
	global_load_lds_dwordx4 v[152:153], off
	s_barrier
	s_waitcnt lgkmcnt(0)
	v_mfma_f32_16x16x32_bf16 v[120:123], v[232:235], v[172:175], v[120:123]
	v_mfma_f32_16x16x32_bf16 v[112:115], v[240:243], v[172:175], v[112:115]
	v_mfma_f32_16x16x32_bf16 v[104:107], v[232:235], v[194:197], v[104:107]
	v_mfma_f32_16x16x32_bf16 v[96:99], v[240:243], v[194:197], v[96:99]
	v_mfma_f32_16x16x32_bf16 v[88:91], v[232:235], v[202:205], v[88:91]
	v_mfma_f32_16x16x32_bf16 v[80:83], v[240:243], v[202:205], v[80:83]
	v_mfma_f32_16x16x32_bf16 v[72:75], v[232:235], v[224:227], v[72:75]
	v_mfma_f32_16x16x32_bf16 v[64:67], v[240:243], v[224:227], v[64:67]
	v_mfma_f32_16x16x32_bf16 v[120:123], v[236:239], v[190:193], v[120:123]
	v_mfma_f32_16x16x32_bf16 v[112:115], v[244:247], v[190:193], v[112:115]
	v_mfma_f32_16x16x32_bf16 v[104:107], v[236:239], v[198:201], v[104:107]
	v_mfma_f32_16x16x32_bf16 v[96:99], v[244:247], v[198:201], v[96:99]
	v_mfma_f32_16x16x32_bf16 v[88:91], v[236:239], v[206:209], v[88:91]
	v_mfma_f32_16x16x32_bf16 v[80:83], v[244:247], v[206:209], v[80:83]
	v_mfma_f32_16x16x32_bf16 v[72:75], v[236:239], v[228:231], v[72:75]
	v_mfma_f32_16x16x32_bf16 v[64:67], v[244:247], v[228:231], v[64:67]
	s_mov_b32 m0, s67
	v_lshl_add_u64 v[152:153], v[250:251], 0, s[86:87]
	s_barrier
	ds_read_b128 v[172:175], v168 offset:49152
	ds_read_b128 v[190:193], v168 offset:50176
	ds_read_b128 v[194:197], v168 offset:51200
	ds_read_b128 v[198:201], v168 offset:52224
	ds_read_b128 v[202:205], v168 offset:53248
	ds_read_b128 v[206:209], v168 offset:54272
	ds_read_b128 v[224:227], v168 offset:55296
	ds_read_b128 v[228:231], v168 offset:56320
	global_load_lds_dwordx4 v[152:153], off
	s_mov_b32 m0, s68
	v_lshl_add_u64 v[152:153], v[252:253], 0, s[86:87]
	global_load_lds_dwordx4 v[152:153], off
	s_barrier
	s_waitcnt lgkmcnt(0)
	v_mfma_f32_16x16x32_bf16 v[60:63], v[136:139], v[172:175], v[60:63]
	v_mfma_f32_16x16x32_bf16 v[52:55], v[144:147], v[172:175], v[52:55]
	v_mfma_f32_16x16x32_bf16 v[44:47], v[136:139], v[194:197], v[44:47]
	v_mfma_f32_16x16x32_bf16 v[36:39], v[144:147], v[194:197], v[36:39]
	v_mfma_f32_16x16x32_bf16 v[28:31], v[136:139], v[202:205], v[28:31]
	v_mfma_f32_16x16x32_bf16 v[20:23], v[144:147], v[202:205], v[20:23]
	v_mfma_f32_16x16x32_bf16 v[12:15], v[136:139], v[224:227], v[12:15]
	v_mfma_f32_16x16x32_bf16 v[4:7], v[144:147], v[224:227], v[4:7]
	v_mfma_f32_16x16x32_bf16 v[60:63], v[140:143], v[190:193], v[60:63]
	v_mfma_f32_16x16x32_bf16 v[52:55], v[148:151], v[190:193], v[52:55]
	v_mfma_f32_16x16x32_bf16 v[44:47], v[140:143], v[198:201], v[44:47]
	v_mfma_f32_16x16x32_bf16 v[36:39], v[148:151], v[198:201], v[36:39]
	v_mfma_f32_16x16x32_bf16 v[28:31], v[140:143], v[206:209], v[28:31]
	v_mfma_f32_16x16x32_bf16 v[20:23], v[148:151], v[206:209], v[20:23]
	v_mfma_f32_16x16x32_bf16 v[12:15], v[140:143], v[228:231], v[12:15]
	v_mfma_f32_16x16x32_bf16 v[4:7], v[148:151], v[228:231], v[4:7]
	s_barrier
	s_add_u32 s28, s28, 0x80080
	s_addc_u32 s29, s29, 0
	s_add_i32 s3, s33, s61
	s_mov_b32 m0, s3
	v_lshl_add_u64 v[136:137], s[28:29], 0, v[184:185]
	global_load_lds_dwordx4 v[136:137], off
	s_add_i32 m0, s3, 0x2000
	v_lshl_add_u64 v[136:137], s[28:29], 0, v[188:189]
	global_load_lds_dwordx4 v[136:137], off
	s_waitcnt vmcnt(6)
	s_barrier
	v_mfma_f32_16x16x32_bf16 v[56:59], v[232:235], v[172:175], v[56:59]
	v_mfma_f32_16x16x32_bf16 v[48:51], v[240:243], v[172:175], v[48:51]
	v_mfma_f32_16x16x32_bf16 v[40:43], v[232:235], v[194:197], v[40:43]
	v_mfma_f32_16x16x32_bf16 v[32:35], v[240:243], v[194:197], v[32:35]
	v_mfma_f32_16x16x32_bf16 v[24:27], v[232:235], v[202:205], v[24:27]
	v_mfma_f32_16x16x32_bf16 v[16:19], v[240:243], v[202:205], v[16:19]
	v_mfma_f32_16x16x32_bf16 v[8:11], v[232:235], v[224:227], v[8:11]
	v_mfma_f32_16x16x32_bf16 v[0:3], v[240:243], v[224:227], v[0:3]
	v_mfma_f32_16x16x32_bf16 v[56:59], v[236:239], v[190:193], v[56:59]
	v_mfma_f32_16x16x32_bf16 v[48:51], v[244:247], v[190:193], v[48:51]
	v_mfma_f32_16x16x32_bf16 v[40:43], v[236:239], v[198:201], v[40:43]
	v_mfma_f32_16x16x32_bf16 v[32:35], v[244:247], v[198:201], v[32:35]
	v_mfma_f32_16x16x32_bf16 v[24:27], v[236:239], v[206:209], v[24:27]
	v_mfma_f32_16x16x32_bf16 v[16:19], v[244:247], v[206:209], v[16:19]
	v_mfma_f32_16x16x32_bf16 v[8:11], v[236:239], v[228:231], v[8:11]
	v_mfma_f32_16x16x32_bf16 v[0:3], v[244:247], v[228:231], v[0:3]
	s_add_i32 vcc_lo, vcc_lo, 2
	s_add_u32 s10, s10, 0x100
	s_addc_u32 s11, s11, 0
	s_add_u32 s93, s93, 0x100
	s_addc_u32 s95, s95, 0
	s_cmp_gt_u32 vcc_lo, 29
	s_cbranch_scc1 .Lrot_exit_in
.Lrot_in:
	s_barrier
.LBB0_234:
	ds_read_b128 v[136:139], v167
	ds_read_b128 v[140:143], v167 offset:1024
	ds_read_b128 v[144:147], v167 offset:2048
	ds_read_b128 v[148:151], v167 offset:3072
	s_add_u32 s3, s10, 0xfff80080
	s_addc_u32 s28, s11, -1
	s_cmp_eq_u32 vcc_lo, 28
	s_cselect_b32 s35, s9, s28
	s_cselect_b32 s34, s89, s3
	s_cselect_b32 s29, s71, s95
	s_cselect_b32 s28, s91, s93
	v_lshl_add_u64 v[152:153], s[10:11], 0, v[132:133]
	s_add_i32 m0, s62, 0xc000
	ds_read_b128 v[172:175], v168
	ds_read_b128 v[190:193], v168 offset:1024
	ds_read_b128 v[194:197], v168 offset:2048
	ds_read_b128 v[198:201], v168 offset:3072
	ds_read_b128 v[202:205], v168 offset:4096
	ds_read_b128 v[206:209], v168 offset:5120
	ds_read_b128 v[224:227], v168 offset:6144
	ds_read_b128 v[228:231], v168 offset:7168
	global_load_lds_dwordx4 v[152:153], off
	s_add_i32 m0, s62, 0xe000
	v_lshl_add_u64 v[152:153], s[10:11], 0, v[134:135]
	global_load_lds_dwordx4 v[152:153], off
	s_waitcnt lgkmcnt(8)
	s_barrier
	s_waitcnt lgkmcnt(0)
	v_mfma_f32_16x16x32_bf16 v[124:127], v[136:139], v[172:175], v[124:127]
	v_mfma_f32_16x16x32_bf16 v[116:119], v[144:147], v[172:175], v[116:119]
	v_mfma_f32_16x16x32_bf16 v[108:111], v[136:139], v[194:197], v[108:111]
	v_mfma_f32_16x16x32_bf16 v[100:103], v[144:147], v[194:197], v[100:103]
	v_mfma_f32_16x16x32_bf16 v[92:95], v[136:139], v[202:205], v[92:95]
	v_mfma_f32_16x16x32_bf16 v[84:87], v[144:147], v[202:205], v[84:87]
	v_mfma_f32_16x16x32_bf16 v[76:79], v[136:139], v[224:227], v[76:79]
	v_mfma_f32_16x16x32_bf16 v[68:71], v[144:147], v[224:227], v[68:71]
	v_mfma_f32_16x16x32_bf16 v[124:127], v[140:143], v[190:193], v[124:127]
	v_mfma_f32_16x16x32_bf16 v[116:119], v[148:151], v[190:193], v[116:119]
	v_mfma_f32_16x16x32_bf16 v[108:111], v[140:143], v[198:201], v[108:111]
	v_mfma_f32_16x16x32_bf16 v[100:103], v[148:151], v[198:201], v[100:103]
	v_mfma_f32_16x16x32_bf16 v[92:95], v[140:143], v[206:209], v[92:95]
	v_mfma_f32_16x16x32_bf16 v[84:87], v[148:151], v[206:209], v[84:87]
	v_mfma_f32_16x16x32_bf16 v[76:79], v[140:143], v[228:231], v[76:79]
	v_mfma_f32_16x16x32_bf16 v[68:71], v[148:151], v[228:231], v[68:71]
	s_barrier
	s_add_i32 s3, s84, s61
	v_lshl_add_u64 v[152:153], s[28:29], 0, v[184:185]
	s_mov_b32 m0, s3
	ds_read_b128 v[232:235], v169
	ds_read_b128 v[236:239], v169 offset:1024
	ds_read_b128 v[240:243], v169 offset:2048
	ds_read_b128 v[244:247], v169 offset:3072
	global_load_lds_dwordx4 v[152:153], off
	s_add_i32 m0, s3, 0x2000
	v_lshl_add_u64 v[248:249], s[28:29], 0, v[188:189]
	global_load_lds_dwordx4 v[248:249], off
	s_barrier
	s_waitcnt lgkmcnt(0)
	v_mfma_f32_16x16x32_bf16 v[120:123], v[232:235], v[172:175], v[120:123]
	v_mfma_f32_16x16x32_bf16 v[112:115], v[240:243], v[172:175], v[112:115]
	v_mfma_f32_16x16x32_bf16 v[104:107], v[232:235], v[194:197], v[104:107]
	v_mfma_f32_16x16x32_bf16 v[96:99], v[240:243], v[194:197], v[96:99]
	v_mfma_f32_16x16x32_bf16 v[88:91], v[232:235], v[202:205], v[88:91]
	v_mfma_f32_16x16x32_bf16 v[80:83], v[240:243], v[202:205], v[80:83]
	v_mfma_f32_16x16x32_bf16 v[72:75], v[232:235], v[224:227], v[72:75]
	v_mfma_f32_16x16x32_bf16 v[64:67], v[240:243], v[224:227], v[64:67]
	v_mfma_f32_16x16x32_bf16 v[120:123], v[236:239], v[190:193], v[120:123]
	v_mfma_f32_16x16x32_bf16 v[112:115], v[244:247], v[190:193], v[112:115]
	v_mfma_f32_16x16x32_bf16 v[104:107], v[236:239], v[198:201], v[104:107]
	v_mfma_f32_16x16x32_bf16 v[96:99], v[244:247], v[198:201], v[96:99]
	v_mfma_f32_16x16x32_bf16 v[88:91], v[236:239], v[206:209], v[88:91]
	v_mfma_f32_16x16x32_bf16 v[80:83], v[244:247], v[206:209], v[80:83]
	v_mfma_f32_16x16x32_bf16 v[72:75], v[236:239], v[228:231], v[72:75]
	v_mfma_f32_16x16x32_bf16 v[64:67], v[244:247], v[228:231], v[64:67]
	s_mov_b32 m0, s62
	v_lshl_add_u64 v[250:251], s[34:35], 0, v[182:183]
	s_barrier
	ds_read_b128 v[172:175], v168 offset:16384
	ds_read_b128 v[190:193], v168 offset:17408
	ds_read_b128 v[194:197], v168 offset:18432
	ds_read_b128 v[198:201], v168 offset:19456
	ds_read_b128 v[202:205], v168 offset:20480
	ds_read_b128 v[206:209], v168 offset:21504
	ds_read_b128 v[224:227], v168 offset:22528
	ds_read_b128 v[228:231], v168 offset:23552
	global_load_lds_dwordx4 v[250:251], off
	s_mov_b32 m0, s63
	v_lshl_add_u64 v[252:253], s[34:35], 0, v[186:187]
	global_load_lds_dwordx4 v[252:253], off
	s_barrier
	s_waitcnt lgkmcnt(0)
	v_mfma_f32_16x16x32_bf16 v[60:63], v[136:139], v[172:175], v[60:63]
	v_mfma_f32_16x16x32_bf16 v[52:55], v[144:147], v[172:175], v[52:55]
	v_mfma_f32_16x16x32_bf16 v[44:47], v[136:139], v[194:197], v[44:47]
	v_mfma_f32_16x16x32_bf16 v[36:39], v[144:147], v[194:197], v[36:39]
	v_mfma_f32_16x16x32_bf16 v[28:31], v[136:139], v[202:205], v[28:31]
	v_mfma_f32_16x16x32_bf16 v[20:23], v[144:147], v[202:205], v[20:23]
	v_mfma_f32_16x16x32_bf16 v[12:15], v[136:139], v[224:227], v[12:15]
	v_mfma_f32_16x16x32_bf16 v[4:7], v[144:147], v[224:227], v[4:7]
	v_mfma_f32_16x16x32_bf16 v[60:63], v[140:143], v[190:193], v[60:63]
	v_mfma_f32_16x16x32_bf16 v[52:55], v[148:151], v[190:193], v[52:55]
	v_mfma_f32_16x16x32_bf16 v[44:47], v[140:143], v[198:201], v[44:47]
	v_mfma_f32_16x16x32_bf16 v[36:39], v[148:151], v[198:201], v[36:39]
	v_mfma_f32_16x16x32_bf16 v[28:31], v[140:143], v[206:209], v[28:31]
	v_mfma_f32_16x16x32_bf16 v[20:23], v[148:151], v[206:209], v[20:23]
	v_mfma_f32_16x16x32_bf16 v[12:15], v[140:143], v[228:231], v[12:15]
	v_mfma_f32_16x16x32_bf16 v[4:7], v[148:151], v[228:231], v[4:7]
	s_barrier
	s_add_u32 s74, s28, 0x80000
	s_addc_u32 s75, s29, 0
	s_add_i32 s3, s85, s61
	s_mov_b32 m0, s3
	v_lshl_add_u64 v[136:137], s[74:75], 0, v[184:185]
	global_load_lds_dwordx4 v[136:137], off
	s_add_i32 m0, s3, 0x2000
	v_lshl_add_u64 v[136:137], s[74:75], 0, v[188:189]
	global_load_lds_dwordx4 v[136:137], off
	s_waitcnt vmcnt(6)
	s_barrier
	v_mfma_f32_16x16x32_bf16 v[56:59], v[232:235], v[172:175], v[56:59]
	v_mfma_f32_16x16x32_bf16 v[48:51], v[240:243], v[172:175], v[48:51]
	v_mfma_f32_16x16x32_bf16 v[40:43], v[232:235], v[194:197], v[40:43]
	v_mfma_f32_16x16x32_bf16 v[32:35], v[240:243], v[194:197], v[32:35]
	v_mfma_f32_16x16x32_bf16 v[24:27], v[232:235], v[202:205], v[24:27]
	v_mfma_f32_16x16x32_bf16 v[16:19], v[240:243], v[202:205], v[16:19]
	v_mfma_f32_16x16x32_bf16 v[8:11], v[232:235], v[224:227], v[8:11]
	v_mfma_f32_16x16x32_bf16 v[0:3], v[240:243], v[224:227], v[0:3]
	v_mfma_f32_16x16x32_bf16 v[56:59], v[236:239], v[190:193], v[56:59]
	v_mfma_f32_16x16x32_bf16 v[48:51], v[244:247], v[190:193], v[48:51]
	v_mfma_f32_16x16x32_bf16 v[40:43], v[236:239], v[198:201], v[40:43]
	v_mfma_f32_16x16x32_bf16 v[32:35], v[244:247], v[198:201], v[32:35]
	v_mfma_f32_16x16x32_bf16 v[24:27], v[236:239], v[206:209], v[24:27]
	v_mfma_f32_16x16x32_bf16 v[16:19], v[244:247], v[206:209], v[16:19]
	v_mfma_f32_16x16x32_bf16 v[8:11], v[236:239], v[228:231], v[8:11]
	v_mfma_f32_16x16x32_bf16 v[0:3], v[244:247], v[228:231], v[0:3]
	s_add_i32 s3, 0, 0x18000
	s_barrier
	ds_read_b128 v[136:139], v171
	ds_read_b128 v[140:143], v171 offset:1024
	ds_read_b128 v[144:147], v171 offset:2048
	ds_read_b128 v[148:151], v171 offset:3072
	s_add_u32 s34, s34, 0x80000
	s_addc_u32 s35, s35, 0
	s_mov_b32 m0, s64
	v_lshl_add_u64 v[232:233], s[34:35], 0, v[182:183]
	ds_read_b128 v[172:175], v168 offset:32768
	ds_read_b128 v[190:193], v168 offset:33792
	ds_read_b128 v[194:197], v168 offset:34816
	ds_read_b128 v[198:201], v168 offset:35840
	ds_read_b128 v[202:205], v168 offset:36864
	ds_read_b128 v[206:209], v168 offset:37888
	ds_read_b128 v[224:227], v168 offset:38912
	ds_read_b128 v[228:231], v168 offset:39936
	global_load_lds_dwordx4 v[232:233], off
	s_mov_b32 m0, s65
	v_lshl_add_u64 v[232:233], s[34:35], 0, v[186:187]
	global_load_lds_dwordx4 v[232:233], off
	s_waitcnt lgkmcnt(8)
	s_barrier
	s_waitcnt lgkmcnt(0)
	v_mfma_f32_16x16x32_bf16 v[124:127], v[136:139], v[172:175], v[124:127]
	v_mfma_f32_16x16x32_bf16 v[116:119], v[144:147], v[172:175], v[116:119]
	v_mfma_f32_16x16x32_bf16 v[108:111], v[136:139], v[194:197], v[108:111]
	v_mfma_f32_16x16x32_bf16 v[100:103], v[144:147], v[194:197], v[100:103]
	v_mfma_f32_16x16x32_bf16 v[92:95], v[136:139], v[202:205], v[92:95]
	v_mfma_f32_16x16x32_bf16 v[84:87], v[144:147], v[202:205], v[84:87]
	v_mfma_f32_16x16x32_bf16 v[76:79], v[136:139], v[224:227], v[76:79]
	v_mfma_f32_16x16x32_bf16 v[68:71], v[144:147], v[224:227], v[68:71]
	v_mfma_f32_16x16x32_bf16 v[124:127], v[140:143], v[190:193], v[124:127]
	v_mfma_f32_16x16x32_bf16 v[116:119], v[148:151], v[190:193], v[116:119]
	v_mfma_f32_16x16x32_bf16 v[108:111], v[140:143], v[198:201], v[108:111]
	v_mfma_f32_16x16x32_bf16 v[100:103], v[148:151], v[198:201], v[100:103]
	v_mfma_f32_16x16x32_bf16 v[92:95], v[140:143], v[206:209], v[92:95]
	v_mfma_f32_16x16x32_bf16 v[84:87], v[148:151], v[206:209], v[84:87]
	v_mfma_f32_16x16x32_bf16 v[76:79], v[140:143], v[228:231], v[76:79]
	v_mfma_f32_16x16x32_bf16 v[68:71], v[148:151], v[228:231], v[68:71]
	s_barrier
	s_add_i32 s33, 0, 0x1c000
	s_add_i32 s3, s3, s61
	v_lshl_add_u64 v[152:153], v[152:153], 0, s[86:87]
	s_mov_b32 m0, s3
	ds_read_b128 v[232:235], v255
	ds_read_b128 v[236:239], v255 offset:1024
	ds_read_b128 v[240:243], v255 offset:2048
	ds_read_b128 v[244:247], v255 offset:3072
	global_load_lds_dwordx4 v[152:153], off
	s_add_i32 m0, s3, 0x2000
	v_lshl_add_u64 v[152:153], v[248:249], 0, s[86:87]
	global_load_lds_dwordx4 v[152:153], off
	s_barrier
	s_waitcnt lgkmcnt(0)
	v_mfma_f32_16x16x32_bf16 v[120:123], v[232:235], v[172:175], v[120:123]
	v_mfma_f32_16x16x32_bf16 v[112:115], v[240:243], v[172:175], v[112:115]
	v_mfma_f32_16x16x32_bf16 v[104:107], v[232:235], v[194:197], v[104:107]
	v_mfma_f32_16x16x32_bf16 v[96:99], v[240:243], v[194:197], v[96:99]
	v_mfma_f32_16x16x32_bf16 v[88:91], v[232:235], v[202:205], v[88:91]
	v_mfma_f32_16x16x32_bf16 v[80:83], v[240:243], v[202:205], v[80:83]
	v_mfma_f32_16x16x32_bf16 v[72:75], v[232:235], v[224:227], v[72:75]
	v_mfma_f32_16x16x32_bf16 v[64:67], v[240:243], v[224:227], v[64:67]
	v_mfma_f32_16x16x32_bf16 v[120:123], v[236:239], v[190:193], v[120:123]
	v_mfma_f32_16x16x32_bf16 v[112:115], v[244:247], v[190:193], v[112:115]
	v_mfma_f32_16x16x32_bf16 v[104:107], v[236:239], v[198:201], v[104:107]
	v_mfma_f32_16x16x32_bf16 v[96:99], v[244:247], v[198:201], v[96:99]
	v_mfma_f32_16x16x32_bf16 v[88:91], v[236:239], v[206:209], v[88:91]
	v_mfma_f32_16x16x32_bf16 v[80:83], v[244:247], v[206:209], v[80:83]
	v_mfma_f32_16x16x32_bf16 v[72:75], v[236:239], v[228:231], v[72:75]
	v_mfma_f32_16x16x32_bf16 v[64:67], v[244:247], v[228:231], v[64:67]
	s_mov_b32 m0, s67
	v_lshl_add_u64 v[152:153], v[250:251], 0, s[86:87]
	s_barrier
	ds_read_b128 v[172:175], v168 offset:49152
	ds_read_b128 v[190:193], v168 offset:50176
	ds_read_b128 v[194:197], v168 offset:51200
	ds_read_b128 v[198:201], v168 offset:52224
	ds_read_b128 v[202:205], v168 offset:53248
	ds_read_b128 v[206:209], v168 offset:54272
	ds_read_b128 v[224:227], v168 offset:55296
	ds_read_b128 v[228:231], v168 offset:56320
	global_load_lds_dwordx4 v[152:153], off
	s_mov_b32 m0, s68
	v_lshl_add_u64 v[152:153], v[252:253], 0, s[86:87]
	global_load_lds_dwordx4 v[152:153], off
	s_barrier
	s_waitcnt lgkmcnt(0)
	v_mfma_f32_16x16x32_bf16 v[60:63], v[136:139], v[172:175], v[60:63]
	v_mfma_f32_16x16x32_bf16 v[52:55], v[144:147], v[172:175], v[52:55]
	v_mfma_f32_16x16x32_bf16 v[44:47], v[136:139], v[194:197], v[44:47]
	v_mfma_f32_16x16x32_bf16 v[36:39], v[144:147], v[194:197], v[36:39]
	v_mfma_f32_16x16x32_bf16 v[28:31], v[136:139], v[202:205], v[28:31]
	v_mfma_f32_16x16x32_bf16 v[20:23], v[144:147], v[202:205], v[20:23]
	v_mfma_f32_16x16x32_bf16 v[12:15], v[136:139], v[224:227], v[12:15]
	v_mfma_f32_16x16x32_bf16 v[4:7], v[144:147], v[224:227], v[4:7]
	v_mfma_f32_16x16x32_bf16 v[60:63], v[140:143], v[190:193], v[60:63]
	v_mfma_f32_16x16x32_bf16 v[52:55], v[148:151], v[190:193], v[52:55]
	v_mfma_f32_16x16x32_bf16 v[44:47], v[140:143], v[198:201], v[44:47]
	v_mfma_f32_16x16x32_bf16 v[36:39], v[148:151], v[198:201], v[36:39]
	v_mfma_f32_16x16x32_bf16 v[28:31], v[140:143], v[206:209], v[28:31]
	v_mfma_f32_16x16x32_bf16 v[20:23], v[148:151], v[206:209], v[20:23]
	v_mfma_f32_16x16x32_bf16 v[12:15], v[140:143], v[228:231], v[12:15]
	v_mfma_f32_16x16x32_bf16 v[4:7], v[148:151], v[228:231], v[4:7]
	s_barrier
	s_add_u32 s28, s28, 0x80080
	s_addc_u32 s29, s29, 0
	s_add_i32 s3, s33, s61
	s_mov_b32 m0, s3
	v_lshl_add_u64 v[136:137], s[28:29], 0, v[184:185]
	global_load_lds_dwordx4 v[136:137], off
	s_add_i32 m0, s3, 0x2000
	v_lshl_add_u64 v[136:137], s[28:29], 0, v[188:189]
	global_load_lds_dwordx4 v[136:137], off
	s_waitcnt vmcnt(6)
	s_barrier
	v_mfma_f32_16x16x32_bf16 v[56:59], v[232:235], v[172:175], v[56:59]
	v_mfma_f32_16x16x32_bf16 v[48:51], v[240:243], v[172:175], v[48:51]
	v_mfma_f32_16x16x32_bf16 v[40:43], v[232:235], v[194:197], v[40:43]
	v_mfma_f32_16x16x32_bf16 v[32:35], v[240:243], v[194:197], v[32:35]
	v_mfma_f32_16x16x32_bf16 v[24:27], v[232:235], v[202:205], v[24:27]
	v_mfma_f32_16x16x32_bf16 v[16:19], v[240:243], v[202:205], v[16:19]
	v_mfma_f32_16x16x32_bf16 v[8:11], v[232:235], v[224:227], v[8:11]
	v_mfma_f32_16x16x32_bf16 v[0:3], v[240:243], v[224:227], v[0:3]
	v_mfma_f32_16x16x32_bf16 v[56:59], v[236:239], v[190:193], v[56:59]
	v_mfma_f32_16x16x32_bf16 v[48:51], v[244:247], v[190:193], v[48:51]
	v_mfma_f32_16x16x32_bf16 v[40:43], v[236:239], v[198:201], v[40:43]
	v_mfma_f32_16x16x32_bf16 v[32:35], v[244:247], v[198:201], v[32:35]
	v_mfma_f32_16x16x32_bf16 v[24:27], v[236:239], v[206:209], v[24:27]
	v_mfma_f32_16x16x32_bf16 v[16:19], v[244:247], v[206:209], v[16:19]
	v_mfma_f32_16x16x32_bf16 v[8:11], v[236:239], v[228:231], v[8:11]
	v_mfma_f32_16x16x32_bf16 v[0:3], v[244:247], v[228:231], v[0:3]
	s_add_i32 vcc_lo, vcc_lo, 2
	s_add_u32 s10, s10, 0x100
	s_addc_u32 s11, s11, 0
	s_add_u32 s93, s93, 0x100
	s_addc_u32 s95, s95, 0
	s_cmp_gt_u32 vcc_lo, 29
	s_cbranch_scc0 .Lrot_in

.LBB0_557:
	s_ashr_i32 s41, s40, 31
	s_xor_b64 s[44:45], s[34:35], -1
	s_lshl_b64 s[46:47], s[40:41], 20
	s_add_u32 s3, s8, s46
	s_addc_u32 s39, s9, s47
	s_ashr_i32 s43, s42, 31
	s_lshl_b64 s[48:49], s[42:43], 1
	s_add_u32 s46, s3, s48
	s_addc_u32 s47, s39, s49
	s_and_b64 s[50:51], s[34:35], exec
	s_cselect_b32 s41, s47, s11
	s_cselect_b32 s43, s46, s10
	s_ashr_i32 s39, s38, 31
	s_lshl_b64 s[50:51], s[38:39], 20
	s_add_u32 s3, s72, s50
	s_addc_u32 s39, s73, s51
	s_add_u32 s48, s3, s48
	s_addc_u32 s49, s39, s49
	s_and_b64 s[34:35], s[34:35], exec
	s_cselect_b32 s39, s49, s29
	s_cselect_b32 s50, s48, s28
	s_add_u32 s10, s10, 0x80080
	s_addc_u32 s11, s11, 0
	s_add_u32 s51, s28, 0x100
	s_addc_u32 s85, s29, 0
	s_mov_b32 s86, 2
	ds_read_b128 v[40:43], v228
	ds_read_b128 v[44:47], v228 offset:1024
	ds_read_b128 v[52:55], v228 offset:2048
	ds_read_b128 v[60:63], v228 offset:3072
	s_add_u32 s3, s10, 0xfff80080
	s_addc_u32 s28, s11, -1
	s_cmp_eq_u32 s84, s86
	s_cselect_b32 s35, s41, s28
	s_cselect_b32 s34, s43, s3
	s_cselect_b32 s29, s39, s85
	s_cselect_b32 s28, s50, s51
	v_lshl_add_u64 v[198:199], s[10:11], 0, v[192:193]
	s_add_i32 m0, s61, 0xc000
	ds_read_b128 v[144:147], v229
	ds_read_b128 v[148:151], v229 offset:1024
	ds_read_b128 v[152:155], v229 offset:2048
	ds_read_b128 v[156:159], v229 offset:3072
	ds_read_b128 v[160:163], v229 offset:4096
	ds_read_b128 v[164:167], v229 offset:5120
	ds_read_b128 v[168:171], v229 offset:6144
	ds_read_b128 v[172:175], v229 offset:7168
	global_load_lds_dwordx4 v[198:199], off
	s_add_i32 m0, s61, 0xe000
	v_lshl_add_u64 v[198:199], s[10:11], 0, v[194:195]
	global_load_lds_dwordx4 v[198:199], off
	s_waitcnt lgkmcnt(8)
	s_barrier
	s_waitcnt lgkmcnt(0)
	v_mfma_f32_16x16x32_bf16 v[140:143], v[40:43], v[144:147], 0
	v_mfma_f32_16x16x32_bf16 v[136:139], v[52:55], v[144:147], 0
	v_mfma_f32_16x16x32_bf16 v[124:127], v[40:43], v[152:155], 0
	v_mfma_f32_16x16x32_bf16 v[120:123], v[52:55], v[152:155], 0
	v_mfma_f32_16x16x32_bf16 v[108:111], v[40:43], v[160:163], 0
	v_mfma_f32_16x16x32_bf16 v[104:107], v[52:55], v[160:163], 0
	v_mfma_f32_16x16x32_bf16 v[92:95], v[40:43], v[168:171], 0
	v_mfma_f32_16x16x32_bf16 v[88:91], v[52:55], v[168:171], 0
	v_mfma_f32_16x16x32_bf16 v[140:143], v[44:47], v[148:151], v[140:143]
	v_mfma_f32_16x16x32_bf16 v[136:139], v[60:63], v[148:151], v[136:139]
	v_mfma_f32_16x16x32_bf16 v[124:127], v[44:47], v[156:159], v[124:127]
	v_mfma_f32_16x16x32_bf16 v[120:123], v[60:63], v[156:159], v[120:123]
	v_mfma_f32_16x16x32_bf16 v[108:111], v[44:47], v[164:167], v[108:111]
	v_mfma_f32_16x16x32_bf16 v[104:107], v[60:63], v[164:167], v[104:107]
	v_mfma_f32_16x16x32_bf16 v[92:95], v[44:47], v[172:175], v[92:95]
	v_mfma_f32_16x16x32_bf16 v[88:91], v[60:63], v[172:175], v[88:91]
	s_barrier
	s_add_i32 s3, s79, s69
	v_lshl_add_u64 v[236:237], s[28:29], 0, v[184:185]
	s_mov_b32 m0, s3
	ds_read_b128 v[198:201], v230
	ds_read_b128 v[202:205], v230 offset:1024
	ds_read_b128 v[206:209], v230 offset:2048
	ds_read_b128 v[232:235], v230 offset:3072
	global_load_lds_dwordx4 v[236:237], off
	s_add_i32 m0, s3, 0x2000
	v_lshl_add_u64 v[238:239], s[28:29], 0, v[188:189]
	global_load_lds_dwordx4 v[238:239], off
	s_barrier
	s_waitcnt lgkmcnt(0)
	v_mfma_f32_16x16x32_bf16 v[132:135], v[198:201], v[144:147], 0
	v_mfma_f32_16x16x32_bf16 v[128:131], v[206:209], v[144:147], 0
	v_mfma_f32_16x16x32_bf16 v[116:119], v[198:201], v[152:155], 0
	v_mfma_f32_16x16x32_bf16 v[112:115], v[206:209], v[152:155], 0
	v_mfma_f32_16x16x32_bf16 v[100:103], v[198:201], v[160:163], 0
	v_mfma_f32_16x16x32_bf16 v[96:99], v[206:209], v[160:163], 0
	v_mfma_f32_16x16x32_bf16 v[84:87], v[198:201], v[168:171], 0
	v_mfma_f32_16x16x32_bf16 v[80:83], v[206:209], v[168:171], 0
	v_mfma_f32_16x16x32_bf16 v[132:135], v[202:205], v[148:151], v[132:135]
	v_mfma_f32_16x16x32_bf16 v[128:131], v[232:235], v[148:151], v[128:131]
	v_mfma_f32_16x16x32_bf16 v[116:119], v[202:205], v[156:159], v[116:119]
	v_mfma_f32_16x16x32_bf16 v[112:115], v[232:235], v[156:159], v[112:115]
	v_mfma_f32_16x16x32_bf16 v[100:103], v[202:205], v[164:167], v[100:103]
	v_mfma_f32_16x16x32_bf16 v[96:99], v[232:235], v[164:167], v[96:99]
	v_mfma_f32_16x16x32_bf16 v[84:87], v[202:205], v[172:175], v[84:87]
	v_mfma_f32_16x16x32_bf16 v[80:83], v[232:235], v[172:175], v[80:83]
	s_mov_b32 m0, s61
	v_lshl_add_u64 v[240:241], s[34:35], 0, v[182:183]
	s_barrier
	ds_read_b128 v[144:147], v229 offset:16384
	ds_read_b128 v[148:151], v229 offset:17408
	ds_read_b128 v[152:155], v229 offset:18432
	ds_read_b128 v[156:159], v229 offset:19456
	ds_read_b128 v[160:163], v229 offset:20480
	ds_read_b128 v[164:167], v229 offset:21504
	ds_read_b128 v[168:171], v229 offset:22528
	ds_read_b128 v[172:175], v229 offset:23552
	global_load_lds_dwordx4 v[240:241], off
	s_mov_b32 m0, s63
	v_lshl_add_u64 v[242:243], s[34:35], 0, v[186:187]
	global_load_lds_dwordx4 v[242:243], off
	s_barrier
	s_waitcnt lgkmcnt(0)
	v_mfma_f32_16x16x32_bf16 v[76:79], v[40:43], v[144:147], 0
	v_mfma_f32_16x16x32_bf16 v[72:75], v[52:55], v[144:147], 0
	v_mfma_f32_16x16x32_bf16 v[56:59], v[40:43], v[152:155], 0
	v_mfma_f32_16x16x32_bf16 v[48:51], v[52:55], v[152:155], 0
	v_mfma_f32_16x16x32_bf16 v[28:31], v[40:43], v[160:163], 0
	v_mfma_f32_16x16x32_bf16 v[24:27], v[52:55], v[160:163], 0
	v_mfma_f32_16x16x32_bf16 v[12:15], v[40:43], v[168:171], 0
	v_mfma_f32_16x16x32_bf16 v[8:11], v[52:55], v[168:171], 0
	v_mfma_f32_16x16x32_bf16 v[76:79], v[44:47], v[148:151], v[76:79]
	v_mfma_f32_16x16x32_bf16 v[72:75], v[60:63], v[148:151], v[72:75]
	v_mfma_f32_16x16x32_bf16 v[56:59], v[44:47], v[156:159], v[56:59]
	v_mfma_f32_16x16x32_bf16 v[48:51], v[60:63], v[156:159], v[48:51]
	v_mfma_f32_16x16x32_bf16 v[28:31], v[44:47], v[164:167], v[28:31]
	v_mfma_f32_16x16x32_bf16 v[24:27], v[60:63], v[164:167], v[24:27]
	v_mfma_f32_16x16x32_bf16 v[12:15], v[44:47], v[172:175], v[12:15]
	v_mfma_f32_16x16x32_bf16 v[8:11], v[60:63], v[172:175], v[8:11]
	s_barrier
	s_add_u32 s88, s28, 0x80000
	s_addc_u32 s89, s29, 0
	s_add_i32 s3, s80, s69
	s_mov_b32 m0, s3
	v_lshl_add_u64 v[40:41], s[88:89], 0, v[184:185]
	global_load_lds_dwordx4 v[40:41], off
	s_add_i32 m0, s3, 0x2000
	v_lshl_add_u64 v[40:41], s[88:89], 0, v[188:189]
	global_load_lds_dwordx4 v[40:41], off
	s_waitcnt vmcnt(6)
	s_barrier
	v_mfma_f32_16x16x32_bf16 v[36:39], v[198:201], v[152:155], 0
	v_mfma_f32_16x16x32_bf16 v[32:35], v[206:209], v[152:155], 0
	v_mfma_f32_16x16x32_bf16 v[20:23], v[198:201], v[160:163], 0
	v_mfma_f32_16x16x32_bf16 v[16:19], v[206:209], v[160:163], 0
	v_mfma_f32_16x16x32_bf16 v[4:7], v[198:201], v[168:171], 0
	v_mfma_f32_16x16x32_bf16 v[0:3], v[206:209], v[168:171], 0
	v_mfma_f32_16x16x32_bf16 v[40:43], v[198:201], v[144:147], 0
	v_mfma_f32_16x16x32_bf16 v[44:47], v[206:209], v[144:147], 0
	v_mfma_f32_16x16x32_bf16 v[36:39], v[202:205], v[156:159], v[36:39]
	v_mfma_f32_16x16x32_bf16 v[32:35], v[232:235], v[156:159], v[32:35]
	v_mfma_f32_16x16x32_bf16 v[20:23], v[202:205], v[164:167], v[20:23]
	v_mfma_f32_16x16x32_bf16 v[16:19], v[232:235], v[164:167], v[16:19]
	v_mfma_f32_16x16x32_bf16 v[4:7], v[202:205], v[172:175], v[4:7]
	v_mfma_f32_16x16x32_bf16 v[0:3], v[232:235], v[172:175], v[0:3]
	v_mfma_f32_16x16x32_bf16 v[40:43], v[202:205], v[148:151], v[40:43]
	v_mfma_f32_16x16x32_bf16 v[44:47], v[232:235], v[148:151], v[44:47]
	s_add_i32 s3, 0, 0x18000
	v_add_u32_e32 v68, s3, v226
	s_barrier
	ds_read_b128 v[52:55], v68
	ds_read_b128 v[60:63], v68 offset:1024
	ds_read_b128 v[64:67], v68 offset:2048
	ds_read_b128 v[68:71], v68 offset:3072
	s_add_u32 s34, s34, 0x80000
	s_addc_u32 s35, s35, 0
	s_mov_b32 m0, s67
	v_lshl_add_u64 v[198:199], s[34:35], 0, v[182:183]
	ds_read_b128 v[144:147], v229 offset:32768
	ds_read_b128 v[148:151], v229 offset:33792
	ds_read_b128 v[152:155], v229 offset:34816
	ds_read_b128 v[156:159], v229 offset:35840
	ds_read_b128 v[160:163], v229 offset:36864
	ds_read_b128 v[164:167], v229 offset:37888
	ds_read_b128 v[168:171], v229 offset:38912
	ds_read_b128 v[172:175], v229 offset:39936
	global_load_lds_dwordx4 v[198:199], off
	s_mov_b32 m0, s70
	v_lshl_add_u64 v[198:199], s[34:35], 0, v[186:187]
	global_load_lds_dwordx4 v[198:199], off
	s_waitcnt lgkmcnt(8)
	s_barrier
	s_waitcnt lgkmcnt(0)
	v_mfma_f32_16x16x32_bf16 v[140:143], v[52:55], v[144:147], v[140:143]
	v_mfma_f32_16x16x32_bf16 v[136:139], v[64:67], v[144:147], v[136:139]
	v_mfma_f32_16x16x32_bf16 v[124:127], v[52:55], v[152:155], v[124:127]
	v_mfma_f32_16x16x32_bf16 v[120:123], v[64:67], v[152:155], v[120:123]
	v_mfma_f32_16x16x32_bf16 v[108:111], v[52:55], v[160:163], v[108:111]
	v_mfma_f32_16x16x32_bf16 v[104:107], v[64:67], v[160:163], v[104:107]
	v_mfma_f32_16x16x32_bf16 v[92:95], v[52:55], v[168:171], v[92:95]
	v_mfma_f32_16x16x32_bf16 v[88:91], v[64:67], v[168:171], v[88:91]
	v_mfma_f32_16x16x32_bf16 v[140:143], v[60:63], v[148:151], v[140:143]
	v_mfma_f32_16x16x32_bf16 v[136:139], v[68:71], v[148:151], v[136:139]
	v_mfma_f32_16x16x32_bf16 v[124:127], v[60:63], v[156:159], v[124:127]
	v_mfma_f32_16x16x32_bf16 v[120:123], v[68:71], v[156:159], v[120:123]
	v_mfma_f32_16x16x32_bf16 v[108:111], v[60:63], v[164:167], v[108:111]
	v_mfma_f32_16x16x32_bf16 v[104:107], v[68:71], v[164:167], v[104:107]
	v_mfma_f32_16x16x32_bf16 v[92:95], v[60:63], v[172:175], v[92:95]
	v_mfma_f32_16x16x32_bf16 v[88:91], v[68:71], v[172:175], v[88:91]
	s_barrier
	s_add_i32 s34, 0, 0x1c000
	s_add_i32 s3, s3, s69
	v_add_u32_e32 v231, s34, v226
	v_lshl_add_u64 v[236:237], v[236:237], 0, s[22:23]
	s_mov_b32 m0, s3
	ds_read_b128 v[198:201], v231
	ds_read_b128 v[202:205], v231 offset:1024
	ds_read_b128 v[206:209], v231 offset:2048
	ds_read_b128 v[232:235], v231 offset:3072
	global_load_lds_dwordx4 v[236:237], off
	s_add_i32 m0, s3, 0x2000
	v_lshl_add_u64 v[236:237], v[238:239], 0, s[22:23]
	global_load_lds_dwordx4 v[236:237], off
	s_barrier
	s_waitcnt lgkmcnt(0)
	v_mfma_f32_16x16x32_bf16 v[132:135], v[198:201], v[144:147], v[132:135]
	v_mfma_f32_16x16x32_bf16 v[128:131], v[206:209], v[144:147], v[128:131]
	v_mfma_f32_16x16x32_bf16 v[116:119], v[198:201], v[152:155], v[116:119]
	v_mfma_f32_16x16x32_bf16 v[112:115], v[206:209], v[152:155], v[112:115]
	v_mfma_f32_16x16x32_bf16 v[100:103], v[198:201], v[160:163], v[100:103]
	v_mfma_f32_16x16x32_bf16 v[96:99], v[206:209], v[160:163], v[96:99]
	v_mfma_f32_16x16x32_bf16 v[84:87], v[198:201], v[168:171], v[84:87]
	v_mfma_f32_16x16x32_bf16 v[80:83], v[206:209], v[168:171], v[80:83]
	v_mfma_f32_16x16x32_bf16 v[132:135], v[202:205], v[148:151], v[132:135]
	v_mfma_f32_16x16x32_bf16 v[128:131], v[232:235], v[148:151], v[128:131]
	v_mfma_f32_16x16x32_bf16 v[116:119], v[202:205], v[156:159], v[116:119]
	v_mfma_f32_16x16x32_bf16 v[112:115], v[232:235], v[156:159], v[112:115]
	v_mfma_f32_16x16x32_bf16 v[100:103], v[202:205], v[164:167], v[100:103]
	v_mfma_f32_16x16x32_bf16 v[96:99], v[232:235], v[164:167], v[96:99]
	v_mfma_f32_16x16x32_bf16 v[84:87], v[202:205], v[172:175], v[84:87]
	v_mfma_f32_16x16x32_bf16 v[80:83], v[232:235], v[172:175], v[80:83]
	s_mov_b32 m0, s71
	v_lshl_add_u64 v[236:237], v[240:241], 0, s[22:23]
	s_barrier
	ds_read_b128 v[144:147], v229 offset:49152
	ds_read_b128 v[148:151], v229 offset:50176
	ds_read_b128 v[152:155], v229 offset:51200
	ds_read_b128 v[156:159], v229 offset:52224
	ds_read_b128 v[160:163], v229 offset:53248
	ds_read_b128 v[164:167], v229 offset:54272
	ds_read_b128 v[168:171], v229 offset:55296
	ds_read_b128 v[172:175], v229 offset:56320
	global_load_lds_dwordx4 v[236:237], off
	s_mov_b32 m0, s74
	v_lshl_add_u64 v[236:237], v[242:243], 0, s[22:23]
	global_load_lds_dwordx4 v[236:237], off
	s_barrier
	s_waitcnt lgkmcnt(0)
	v_mfma_f32_16x16x32_bf16 v[76:79], v[52:55], v[144:147], v[76:79]
	v_mfma_f32_16x16x32_bf16 v[72:75], v[64:67], v[144:147], v[72:75]
	v_mfma_f32_16x16x32_bf16 v[56:59], v[52:55], v[152:155], v[56:59]
	v_mfma_f32_16x16x32_bf16 v[48:51], v[64:67], v[152:155], v[48:51]
	v_mfma_f32_16x16x32_bf16 v[28:31], v[52:55], v[160:163], v[28:31]
	v_mfma_f32_16x16x32_bf16 v[24:27], v[64:67], v[160:163], v[24:27]
	v_mfma_f32_16x16x32_bf16 v[12:15], v[52:55], v[168:171], v[12:15]
	v_mfma_f32_16x16x32_bf16 v[8:11], v[64:67], v[168:171], v[8:11]
	v_mfma_f32_16x16x32_bf16 v[76:79], v[60:63], v[148:151], v[76:79]
	v_mfma_f32_16x16x32_bf16 v[72:75], v[68:71], v[148:151], v[72:75]
	v_mfma_f32_16x16x32_bf16 v[56:59], v[60:63], v[156:159], v[56:59]
	v_mfma_f32_16x16x32_bf16 v[48:51], v[68:71], v[156:159], v[48:51]
	v_mfma_f32_16x16x32_bf16 v[28:31], v[60:63], v[164:167], v[28:31]
	v_mfma_f32_16x16x32_bf16 v[24:27], v[68:71], v[164:167], v[24:27]
	v_mfma_f32_16x16x32_bf16 v[12:15], v[60:63], v[172:175], v[12:15]
	v_mfma_f32_16x16x32_bf16 v[8:11], v[68:71], v[172:175], v[8:11]
	s_barrier
	s_add_u32 s28, s28, 0x80080
	s_addc_u32 s29, s29, 0
	s_add_i32 s3, s34, s69
	s_mov_b32 m0, s3
	v_lshl_add_u64 v[52:53], s[28:29], 0, v[184:185]
	global_load_lds_dwordx4 v[52:53], off
	s_add_i32 m0, s3, 0x2000
	v_lshl_add_u64 v[52:53], s[28:29], 0, v[188:189]
	global_load_lds_dwordx4 v[52:53], off
	s_waitcnt vmcnt(6)
	s_barrier
	v_mfma_f32_16x16x32_bf16 v[40:43], v[198:201], v[144:147], v[40:43]
	v_mfma_f32_16x16x32_bf16 v[68:71], v[202:205], v[148:151], v[40:43]
	v_mfma_f32_16x16x32_bf16 v[40:43], v[206:209], v[144:147], v[44:47]
	v_mfma_f32_16x16x32_bf16 v[36:39], v[198:201], v[152:155], v[36:39]
	v_mfma_f32_16x16x32_bf16 v[32:35], v[206:209], v[152:155], v[32:35]
	v_mfma_f32_16x16x32_bf16 v[20:23], v[198:201], v[160:163], v[20:23]
	v_mfma_f32_16x16x32_bf16 v[16:19], v[206:209], v[160:163], v[16:19]
	v_mfma_f32_16x16x32_bf16 v[4:7], v[198:201], v[168:171], v[4:7]
	v_mfma_f32_16x16x32_bf16 v[0:3], v[206:209], v[168:171], v[0:3]
	v_mfma_f32_16x16x32_bf16 v[64:67], v[232:235], v[148:151], v[40:43]
	v_mfma_f32_16x16x32_bf16 v[36:39], v[202:205], v[156:159], v[36:39]
	v_mfma_f32_16x16x32_bf16 v[32:35], v[232:235], v[156:159], v[32:35]
	v_mfma_f32_16x16x32_bf16 v[20:23], v[202:205], v[164:167], v[20:23]
	v_mfma_f32_16x16x32_bf16 v[16:19], v[232:235], v[164:167], v[16:19]
	v_mfma_f32_16x16x32_bf16 v[4:7], v[202:205], v[172:175], v[4:7]
	v_mfma_f32_16x16x32_bf16 v[0:3], v[232:235], v[172:175], v[0:3]
	s_add_i32 s3, s86, 2
	s_add_u32 s10, s10, 0x100
	s_addc_u32 s11, s11, 0
	s_add_u32 s51, s51, 0x100
	s_addc_u32 s85, s85, 0
	s_cmp_ge_u32 s86, s84
	s_mov_b32 s86, s3
	s_cbranch_scc1 .Lrot_exit_glu

.LBB0_558:
	ds_read_b128 v[40:43], v228
	ds_read_b128 v[44:47], v228 offset:1024
	ds_read_b128 v[52:55], v228 offset:2048
	ds_read_b128 v[60:63], v228 offset:3072
	s_add_u32 s3, s10, 0xfff80080
	s_addc_u32 s28, s11, -1
	s_cmp_eq_u32 s84, s86
	s_cselect_b32 s35, s41, s28
	s_cselect_b32 s34, s43, s3
	s_cselect_b32 s29, s39, s85
	s_cselect_b32 s28, s50, s51
	v_lshl_add_u64 v[198:199], s[10:11], 0, v[192:193]
	s_add_i32 m0, s61, 0xc000
	ds_read_b128 v[144:147], v229
	ds_read_b128 v[148:151], v229 offset:1024
	ds_read_b128 v[152:155], v229 offset:2048
	ds_read_b128 v[156:159], v229 offset:3072
	ds_read_b128 v[160:163], v229 offset:4096
	ds_read_b128 v[164:167], v229 offset:5120
	ds_read_b128 v[168:171], v229 offset:6144
	ds_read_b128 v[172:175], v229 offset:7168
	global_load_lds_dwordx4 v[198:199], off
	s_add_i32 m0, s61, 0xe000
	v_lshl_add_u64 v[198:199], s[10:11], 0, v[194:195]
	global_load_lds_dwordx4 v[198:199], off
	s_waitcnt lgkmcnt(8)
	s_barrier
	s_waitcnt lgkmcnt(0)
	v_mfma_f32_16x16x32_bf16 v[140:143], v[40:43], v[144:147], v[140:143]
	v_mfma_f32_16x16x32_bf16 v[136:139], v[52:55], v[144:147], v[136:139]
	v_mfma_f32_16x16x32_bf16 v[124:127], v[40:43], v[152:155], v[124:127]
	v_mfma_f32_16x16x32_bf16 v[120:123], v[52:55], v[152:155], v[120:123]
	v_mfma_f32_16x16x32_bf16 v[108:111], v[40:43], v[160:163], v[108:111]
	v_mfma_f32_16x16x32_bf16 v[104:107], v[52:55], v[160:163], v[104:107]
	v_mfma_f32_16x16x32_bf16 v[92:95], v[40:43], v[168:171], v[92:95]
	v_mfma_f32_16x16x32_bf16 v[88:91], v[52:55], v[168:171], v[88:91]
	v_mfma_f32_16x16x32_bf16 v[140:143], v[44:47], v[148:151], v[140:143]
	v_mfma_f32_16x16x32_bf16 v[136:139], v[60:63], v[148:151], v[136:139]
	v_mfma_f32_16x16x32_bf16 v[124:127], v[44:47], v[156:159], v[124:127]
	v_mfma_f32_16x16x32_bf16 v[120:123], v[60:63], v[156:159], v[120:123]
	v_mfma_f32_16x16x32_bf16 v[108:111], v[44:47], v[164:167], v[108:111]
	v_mfma_f32_16x16x32_bf16 v[104:107], v[60:63], v[164:167], v[104:107]
	v_mfma_f32_16x16x32_bf16 v[92:95], v[44:47], v[172:175], v[92:95]
	v_mfma_f32_16x16x32_bf16 v[88:91], v[60:63], v[172:175], v[88:91]
	s_barrier
	s_add_i32 s3, s79, s69
	v_lshl_add_u64 v[236:237], s[28:29], 0, v[184:185]
	s_mov_b32 m0, s3
	ds_read_b128 v[198:201], v230
	ds_read_b128 v[202:205], v230 offset:1024
	ds_read_b128 v[206:209], v230 offset:2048
	ds_read_b128 v[232:235], v230 offset:3072
	global_load_lds_dwordx4 v[236:237], off
	s_add_i32 m0, s3, 0x2000
	v_lshl_add_u64 v[238:239], s[28:29], 0, v[188:189]
	global_load_lds_dwordx4 v[238:239], off
	s_barrier
	s_waitcnt lgkmcnt(0)
	v_mfma_f32_16x16x32_bf16 v[132:135], v[198:201], v[144:147], v[132:135]
	v_mfma_f32_16x16x32_bf16 v[128:131], v[206:209], v[144:147], v[128:131]
	v_mfma_f32_16x16x32_bf16 v[116:119], v[198:201], v[152:155], v[116:119]
	v_mfma_f32_16x16x32_bf16 v[112:115], v[206:209], v[152:155], v[112:115]
	v_mfma_f32_16x16x32_bf16 v[100:103], v[198:201], v[160:163], v[100:103]
	v_mfma_f32_16x16x32_bf16 v[96:99], v[206:209], v[160:163], v[96:99]
	v_mfma_f32_16x16x32_bf16 v[84:87], v[198:201], v[168:171], v[84:87]
	v_mfma_f32_16x16x32_bf16 v[80:83], v[206:209], v[168:171], v[80:83]
	v_mfma_f32_16x16x32_bf16 v[132:135], v[202:205], v[148:151], v[132:135]
	v_mfma_f32_16x16x32_bf16 v[128:131], v[232:235], v[148:151], v[128:131]
	v_mfma_f32_16x16x32_bf16 v[116:119], v[202:205], v[156:159], v[116:119]
	v_mfma_f32_16x16x32_bf16 v[112:115], v[232:235], v[156:159], v[112:115]
	v_mfma_f32_16x16x32_bf16 v[100:103], v[202:205], v[164:167], v[100:103]
	v_mfma_f32_16x16x32_bf16 v[96:99], v[232:235], v[164:167], v[96:99]
	v_mfma_f32_16x16x32_bf16 v[84:87], v[202:205], v[172:175], v[84:87]
	v_mfma_f32_16x16x32_bf16 v[80:83], v[232:235], v[172:175], v[80:83]
	s_mov_b32 m0, s61
	v_lshl_add_u64 v[240:241], s[34:35], 0, v[182:183]
	s_barrier
	ds_read_b128 v[144:147], v229 offset:16384
	ds_read_b128 v[148:151], v229 offset:17408
	ds_read_b128 v[152:155], v229 offset:18432
	ds_read_b128 v[156:159], v229 offset:19456
	ds_read_b128 v[160:163], v229 offset:20480
	ds_read_b128 v[164:167], v229 offset:21504
	ds_read_b128 v[168:171], v229 offset:22528
	ds_read_b128 v[172:175], v229 offset:23552
	global_load_lds_dwordx4 v[240:241], off
	s_mov_b32 m0, s63
	v_lshl_add_u64 v[242:243], s[34:35], 0, v[186:187]
	global_load_lds_dwordx4 v[242:243], off
	s_barrier
	s_waitcnt lgkmcnt(0)
	v_mfma_f32_16x16x32_bf16 v[76:79], v[40:43], v[144:147], v[76:79]
	v_mfma_f32_16x16x32_bf16 v[72:75], v[52:55], v[144:147], v[72:75]
	v_mfma_f32_16x16x32_bf16 v[56:59], v[40:43], v[152:155], v[56:59]
	v_mfma_f32_16x16x32_bf16 v[48:51], v[52:55], v[152:155], v[48:51]
	v_mfma_f32_16x16x32_bf16 v[28:31], v[40:43], v[160:163], v[28:31]
	v_mfma_f32_16x16x32_bf16 v[24:27], v[52:55], v[160:163], v[24:27]
	v_mfma_f32_16x16x32_bf16 v[12:15], v[40:43], v[168:171], v[12:15]
	v_mfma_f32_16x16x32_bf16 v[8:11], v[52:55], v[168:171], v[8:11]
	v_mfma_f32_16x16x32_bf16 v[76:79], v[44:47], v[148:151], v[76:79]
	v_mfma_f32_16x16x32_bf16 v[72:75], v[60:63], v[148:151], v[72:75]
	v_mfma_f32_16x16x32_bf16 v[56:59], v[44:47], v[156:159], v[56:59]
	v_mfma_f32_16x16x32_bf16 v[48:51], v[60:63], v[156:159], v[48:51]
	v_mfma_f32_16x16x32_bf16 v[28:31], v[44:47], v[164:167], v[28:31]
	v_mfma_f32_16x16x32_bf16 v[24:27], v[60:63], v[164:167], v[24:27]
	v_mfma_f32_16x16x32_bf16 v[12:15], v[44:47], v[172:175], v[12:15]
	v_mfma_f32_16x16x32_bf16 v[8:11], v[60:63], v[172:175], v[8:11]
	s_barrier
	s_add_u32 s88, s28, 0x80000
	s_addc_u32 s89, s29, 0
	s_add_i32 s3, s80, s69
	s_mov_b32 m0, s3
	v_lshl_add_u64 v[40:41], s[88:89], 0, v[184:185]
	global_load_lds_dwordx4 v[40:41], off
	s_add_i32 m0, s3, 0x2000
	v_lshl_add_u64 v[40:41], s[88:89], 0, v[188:189]
	global_load_lds_dwordx4 v[40:41], off
	s_waitcnt vmcnt(6)
	s_barrier
	v_mfma_f32_16x16x32_bf16 v[36:39], v[198:201], v[152:155], v[36:39]
	v_mfma_f32_16x16x32_bf16 v[32:35], v[206:209], v[152:155], v[32:35]
	v_mfma_f32_16x16x32_bf16 v[20:23], v[198:201], v[160:163], v[20:23]
	v_mfma_f32_16x16x32_bf16 v[16:19], v[206:209], v[160:163], v[16:19]
	v_mfma_f32_16x16x32_bf16 v[4:7], v[198:201], v[168:171], v[4:7]
	v_mfma_f32_16x16x32_bf16 v[0:3], v[206:209], v[168:171], v[0:3]
	v_mfma_f32_16x16x32_bf16 v[40:43], v[198:201], v[144:147], v[68:71]
	v_mfma_f32_16x16x32_bf16 v[44:47], v[206:209], v[144:147], v[64:67]
	v_mfma_f32_16x16x32_bf16 v[36:39], v[202:205], v[156:159], v[36:39]
	v_mfma_f32_16x16x32_bf16 v[32:35], v[232:235], v[156:159], v[32:35]
	v_mfma_f32_16x16x32_bf16 v[20:23], v[202:205], v[164:167], v[20:23]
	v_mfma_f32_16x16x32_bf16 v[16:19], v[232:235], v[164:167], v[16:19]
	v_mfma_f32_16x16x32_bf16 v[4:7], v[202:205], v[172:175], v[4:7]
	v_mfma_f32_16x16x32_bf16 v[0:3], v[232:235], v[172:175], v[0:3]
	v_mfma_f32_16x16x32_bf16 v[40:43], v[202:205], v[148:151], v[40:43]
	v_mfma_f32_16x16x32_bf16 v[44:47], v[232:235], v[148:151], v[44:47]
	s_add_i32 s3, 0, 0x18000
	v_add_u32_e32 v68, s3, v226
	s_barrier
	ds_read_b128 v[52:55], v68
	ds_read_b128 v[60:63], v68 offset:1024
	ds_read_b128 v[64:67], v68 offset:2048
	ds_read_b128 v[68:71], v68 offset:3072
	s_add_u32 s34, s34, 0x80000
	s_addc_u32 s35, s35, 0
	s_mov_b32 m0, s67
	v_lshl_add_u64 v[198:199], s[34:35], 0, v[182:183]
	ds_read_b128 v[144:147], v229 offset:32768
	ds_read_b128 v[148:151], v229 offset:33792
	ds_read_b128 v[152:155], v229 offset:34816
	ds_read_b128 v[156:159], v229 offset:35840
	ds_read_b128 v[160:163], v229 offset:36864
	ds_read_b128 v[164:167], v229 offset:37888
	ds_read_b128 v[168:171], v229 offset:38912
	ds_read_b128 v[172:175], v229 offset:39936
	global_load_lds_dwordx4 v[198:199], off
	s_mov_b32 m0, s70
	v_lshl_add_u64 v[198:199], s[34:35], 0, v[186:187]
	global_load_lds_dwordx4 v[198:199], off
	s_waitcnt lgkmcnt(8)
	s_barrier
	s_waitcnt lgkmcnt(0)
	v_mfma_f32_16x16x32_bf16 v[140:143], v[52:55], v[144:147], v[140:143]
	v_mfma_f32_16x16x32_bf16 v[136:139], v[64:67], v[144:147], v[136:139]
	v_mfma_f32_16x16x32_bf16 v[124:127], v[52:55], v[152:155], v[124:127]
	v_mfma_f32_16x16x32_bf16 v[120:123], v[64:67], v[152:155], v[120:123]
	v_mfma_f32_16x16x32_bf16 v[108:111], v[52:55], v[160:163], v[108:111]
	v_mfma_f32_16x16x32_bf16 v[104:107], v[64:67], v[160:163], v[104:107]
	v_mfma_f32_16x16x32_bf16 v[92:95], v[52:55], v[168:171], v[92:95]
	v_mfma_f32_16x16x32_bf16 v[88:91], v[64:67], v[168:171], v[88:91]
	v_mfma_f32_16x16x32_bf16 v[140:143], v[60:63], v[148:151], v[140:143]
	v_mfma_f32_16x16x32_bf16 v[136:139], v[68:71], v[148:151], v[136:139]
	v_mfma_f32_16x16x32_bf16 v[124:127], v[60:63], v[156:159], v[124:127]
	v_mfma_f32_16x16x32_bf16 v[120:123], v[68:71], v[156:159], v[120:123]
	v_mfma_f32_16x16x32_bf16 v[108:111], v[60:63], v[164:167], v[108:111]
	v_mfma_f32_16x16x32_bf16 v[104:107], v[68:71], v[164:167], v[104:107]
	v_mfma_f32_16x16x32_bf16 v[92:95], v[60:63], v[172:175], v[92:95]
	v_mfma_f32_16x16x32_bf16 v[88:91], v[68:71], v[172:175], v[88:91]
	s_barrier
	s_add_i32 s34, 0, 0x1c000
	s_add_i32 s3, s3, s69
	v_add_u32_e32 v231, s34, v226
	v_lshl_add_u64 v[236:237], v[236:237], 0, s[22:23]
	s_mov_b32 m0, s3
	ds_read_b128 v[198:201], v231
	ds_read_b128 v[202:205], v231 offset:1024
	ds_read_b128 v[206:209], v231 offset:2048
	ds_read_b128 v[232:235], v231 offset:3072
	global_load_lds_dwordx4 v[236:237], off
	s_add_i32 m0, s3, 0x2000
	v_lshl_add_u64 v[236:237], v[238:239], 0, s[22:23]
	global_load_lds_dwordx4 v[236:237], off
	s_barrier
	s_waitcnt lgkmcnt(0)
	v_mfma_f32_16x16x32_bf16 v[132:135], v[198:201], v[144:147], v[132:135]
	v_mfma_f32_16x16x32_bf16 v[128:131], v[206:209], v[144:147], v[128:131]
	v_mfma_f32_16x16x32_bf16 v[116:119], v[198:201], v[152:155], v[116:119]
	v_mfma_f32_16x16x32_bf16 v[112:115], v[206:209], v[152:155], v[112:115]
	v_mfma_f32_16x16x32_bf16 v[100:103], v[198:201], v[160:163], v[100:103]
	v_mfma_f32_16x16x32_bf16 v[96:99], v[206:209], v[160:163], v[96:99]
	v_mfma_f32_16x16x32_bf16 v[84:87], v[198:201], v[168:171], v[84:87]
	v_mfma_f32_16x16x32_bf16 v[80:83], v[206:209], v[168:171], v[80:83]
	v_mfma_f32_16x16x32_bf16 v[132:135], v[202:205], v[148:151], v[132:135]
	v_mfma_f32_16x16x32_bf16 v[128:131], v[232:235], v[148:151], v[128:131]
	v_mfma_f32_16x16x32_bf16 v[116:119], v[202:205], v[156:159], v[116:119]
	v_mfma_f32_16x16x32_bf16 v[112:115], v[232:235], v[156:159], v[112:115]
	v_mfma_f32_16x16x32_bf16 v[100:103], v[202:205], v[164:167], v[100:103]
	v_mfma_f32_16x16x32_bf16 v[96:99], v[232:235], v[164:167], v[96:99]
	v_mfma_f32_16x16x32_bf16 v[84:87], v[202:205], v[172:175], v[84:87]
	v_mfma_f32_16x16x32_bf16 v[80:83], v[232:235], v[172:175], v[80:83]
	s_mov_b32 m0, s71
	v_lshl_add_u64 v[236:237], v[240:241], 0, s[22:23]
	s_barrier
	ds_read_b128 v[144:147], v229 offset:49152
	ds_read_b128 v[148:151], v229 offset:50176
	ds_read_b128 v[152:155], v229 offset:51200
	ds_read_b128 v[156:159], v229 offset:52224
	ds_read_b128 v[160:163], v229 offset:53248
	ds_read_b128 v[164:167], v229 offset:54272
	ds_read_b128 v[168:171], v229 offset:55296
	ds_read_b128 v[172:175], v229 offset:56320
	global_load_lds_dwordx4 v[236:237], off
	s_mov_b32 m0, s74
	v_lshl_add_u64 v[236:237], v[242:243], 0, s[22:23]
	global_load_lds_dwordx4 v[236:237], off
	s_barrier
	s_waitcnt lgkmcnt(0)
	v_mfma_f32_16x16x32_bf16 v[76:79], v[52:55], v[144:147], v[76:79]
	v_mfma_f32_16x16x32_bf16 v[72:75], v[64:67], v[144:147], v[72:75]
	v_mfma_f32_16x16x32_bf16 v[56:59], v[52:55], v[152:155], v[56:59]
	v_mfma_f32_16x16x32_bf16 v[48:51], v[64:67], v[152:155], v[48:51]
	v_mfma_f32_16x16x32_bf16 v[28:31], v[52:55], v[160:163], v[28:31]
	v_mfma_f32_16x16x32_bf16 v[24:27], v[64:67], v[160:163], v[24:27]
	v_mfma_f32_16x16x32_bf16 v[12:15], v[52:55], v[168:171], v[12:15]
	v_mfma_f32_16x16x32_bf16 v[8:11], v[64:67], v[168:171], v[8:11]
	v_mfma_f32_16x16x32_bf16 v[76:79], v[60:63], v[148:151], v[76:79]
	v_mfma_f32_16x16x32_bf16 v[72:75], v[68:71], v[148:151], v[72:75]
	v_mfma_f32_16x16x32_bf16 v[56:59], v[60:63], v[156:159], v[56:59]
	v_mfma_f32_16x16x32_bf16 v[48:51], v[68:71], v[156:159], v[48:51]
	v_mfma_f32_16x16x32_bf16 v[28:31], v[60:63], v[164:167], v[28:31]
	v_mfma_f32_16x16x32_bf16 v[24:27], v[68:71], v[164:167], v[24:27]
	v_mfma_f32_16x16x32_bf16 v[12:15], v[60:63], v[172:175], v[12:15]
	v_mfma_f32_16x16x32_bf16 v[8:11], v[68:71], v[172:175], v[8:11]
	s_barrier
	s_add_u32 s28, s28, 0x80080
	s_addc_u32 s29, s29, 0
	s_add_i32 s3, s34, s69
	s_mov_b32 m0, s3
	v_lshl_add_u64 v[52:53], s[28:29], 0, v[184:185]
	global_load_lds_dwordx4 v[52:53], off
	s_add_i32 m0, s3, 0x2000
	v_lshl_add_u64 v[52:53], s[28:29], 0, v[188:189]
	global_load_lds_dwordx4 v[52:53], off
	s_waitcnt vmcnt(6)
	s_barrier
	v_mfma_f32_16x16x32_bf16 v[40:43], v[198:201], v[144:147], v[40:43]
	v_mfma_f32_16x16x32_bf16 v[68:71], v[202:205], v[148:151], v[40:43]
	v_mfma_f32_16x16x32_bf16 v[40:43], v[206:209], v[144:147], v[44:47]
	v_mfma_f32_16x16x32_bf16 v[36:39], v[198:201], v[152:155], v[36:39]
	v_mfma_f32_16x16x32_bf16 v[32:35], v[206:209], v[152:155], v[32:35]
	v_mfma_f32_16x16x32_bf16 v[20:23], v[198:201], v[160:163], v[20:23]
	v_mfma_f32_16x16x32_bf16 v[16:19], v[206:209], v[160:163], v[16:19]
	v_mfma_f32_16x16x32_bf16 v[4:7], v[198:201], v[168:171], v[4:7]
	v_mfma_f32_16x16x32_bf16 v[0:3], v[206:209], v[168:171], v[0:3]
	v_mfma_f32_16x16x32_bf16 v[64:67], v[232:235], v[148:151], v[40:43]
	v_mfma_f32_16x16x32_bf16 v[36:39], v[202:205], v[156:159], v[36:39]
	v_mfma_f32_16x16x32_bf16 v[32:35], v[232:235], v[156:159], v[32:35]
	v_mfma_f32_16x16x32_bf16 v[20:23], v[202:205], v[164:167], v[20:23]
	v_mfma_f32_16x16x32_bf16 v[16:19], v[232:235], v[164:167], v[16:19]
	v_mfma_f32_16x16x32_bf16 v[4:7], v[202:205], v[172:175], v[4:7]
	v_mfma_f32_16x16x32_bf16 v[0:3], v[232:235], v[172:175], v[0:3]
	s_add_i32 s3, s86, 2
	s_add_u32 s10, s10, 0x100
	s_addc_u32 s11, s11, 0
	s_add_u32 s51, s51, 0x100
	s_addc_u32 s85, s85, 0
	s_cmp_ge_u32 s86, s84
	s_mov_b32 s86, s3
	s_cbranch_scc0 .Lrot_glu

.LBB0_639:
	s_mov_b64 s[34:35], s[8:9]
	s_add_u32 s83, s34, 0x100
	s_addc_u32 s84, s35, 0
	v_add_co_u32_e64 v56, s[26:27], s80, 1
	s_and_b64 s[8:9], s[26:27], exec
	s_cselect_b32 s10, s4, s69
	s_cselect_b32 s82, s66, 0
	s_cmp_gt_i32 s80, 0
	s_cselect_b64 s[20:21], -1, 0
	s_ashr_i32 s11, s10, 31
	s_lshl_b64 s[8:9], s[10:11], 21
	s_add_u32 s3, s56, s8
	s_addc_u32 s8, s57, s9
	s_lshl_b32 s9, s82, 1
	s_add_u32 s24, s3, s9
	s_addc_u32 s25, s8, 0
	s_add_u32 s8, s42, s9
	s_addc_u32 s9, s43, 0
	s_cmp_lt_i32 s80, 1
	s_cselect_b64 s[28:29], -1, 0
	s_and_b64 s[36:37], s[28:29], exec
	s_cselect_b32 s11, s25, s23
	s_cselect_b32 s85, s24, s22
	s_cselect_b32 s86, s9, s35
	s_cselect_b32 s87, s8, s34
	s_lshl_b32 s3, s49, 7
	s_addk_i32 s3, 0xfc00
	v_readfirstlane_b32 s81, v56
	v_lshl_add_u64 v[58:59], s[22:23], 0, v[142:143]
	v_lshl_add_u64 v[146:147], s[22:23], 0, v[144:145]
	s_add_u32 s88, s3, 0x300
	s_mov_b64 s[34:35], 0
	s_mov_b32 s89, 0
	s_add_i32 s89, s89, 2
	v_add_u32_e32 v56, s71, v139
	s_add_u32 s3, s22, s34
	ds_read_b128 v[150:153], v56
	ds_read_b128 v[154:157], v56 offset:1024
	ds_read_b128 v[158:161], v56 offset:2048
	ds_read_b128 v[162:165], v56 offset:3072
	s_addc_u32 s36, s23, s35
	s_add_u32 s3, s3, 0x100
	s_addc_u32 s36, s36, 0
	s_add_u32 s90, s83, s34
	s_addc_u32 s37, s84, s35
	s_cmp_eq_u32 s88, s34
	s_cselect_b32 s39, s11, s36
	s_cselect_b32 s38, s85, s3
	s_cselect_b32 s37, s86, s37
	s_cselect_b32 s36, s87, s90
	s_mov_b32 m0, s73
	v_lshl_add_u64 v[174:175], v[58:59], 0, s[34:35]
	ds_read_b128 v[166:169], v133
	ds_read_b128 v[170:173], v133 offset:1024
	ds_read_b128 v[182:185], v133 offset:2048
	ds_read_b128 v[186:189], v133 offset:3072
	ds_read_b128 v[190:193], v133 offset:4096
	ds_read_b128 v[194:197], v133 offset:5120
	ds_read_b128 v[198:201], v133 offset:6144
	ds_read_b128 v[202:205], v133 offset:7168
	global_load_lds_dwordx4 v[174:175], off
	s_mov_b32 m0, s74
	v_lshl_add_u64 v[174:175], v[146:147], 0, s[34:35]
	global_load_lds_dwordx4 v[174:175], off
	s_waitcnt lgkmcnt(8)
	s_barrier
	s_waitcnt lgkmcnt(0)
	v_mfma_f32_16x16x32_bf16 v[128:131], v[150:153], v[166:169], 0
	v_mfma_f32_16x16x32_bf16 v[124:127], v[158:161], v[166:169], 0
	v_mfma_f32_16x16x32_bf16 v[112:115], v[150:153], v[182:185], 0
	v_mfma_f32_16x16x32_bf16 v[108:111], v[158:161], v[182:185], 0
	v_mfma_f32_16x16x32_bf16 v[96:99], v[150:153], v[190:193], 0
	v_mfma_f32_16x16x32_bf16 v[92:95], v[158:161], v[190:193], 0
	v_mfma_f32_16x16x32_bf16 v[80:83], v[150:153], v[198:201], 0
	v_mfma_f32_16x16x32_bf16 v[76:79], v[158:161], v[198:201], 0
	v_mfma_f32_16x16x32_bf16 v[128:131], v[154:157], v[170:173], v[128:131]
	v_mfma_f32_16x16x32_bf16 v[124:127], v[162:165], v[170:173], v[124:127]
	v_mfma_f32_16x16x32_bf16 v[112:115], v[154:157], v[186:189], v[112:115]
	v_mfma_f32_16x16x32_bf16 v[108:111], v[162:165], v[186:189], v[108:111]
	v_mfma_f32_16x16x32_bf16 v[96:99], v[154:157], v[194:197], v[96:99]
	v_mfma_f32_16x16x32_bf16 v[92:95], v[162:165], v[194:197], v[92:95]
	v_mfma_f32_16x16x32_bf16 v[80:83], v[154:157], v[202:205], v[80:83]
	v_mfma_f32_16x16x32_bf16 v[76:79], v[162:165], v[202:205], v[76:79]
	s_barrier
	s_mov_b32 m0, s75
	v_add_u32_e32 v56, s72, v139
	v_lshl_add_u64 v[174:175], s[36:37], 0, v[134:135]
	ds_read_b128 v[206:209], v56
	ds_read_b128 v[214:217], v56 offset:1024
	ds_read_b128 v[218:221], v56 offset:2048
	ds_read_b128 v[222:225], v56 offset:3072
	global_load_lds_dwordx4 v[174:175], off
	s_mov_b32 m0, s76
	v_lshl_add_u64 v[226:227], s[36:37], 0, v[136:137]
	global_load_lds_dwordx4 v[226:227], off
	s_barrier
	s_waitcnt lgkmcnt(0)
	v_mfma_f32_16x16x32_bf16 v[120:123], v[206:209], v[166:169], 0
	v_mfma_f32_16x16x32_bf16 v[116:119], v[218:221], v[166:169], 0
	v_mfma_f32_16x16x32_bf16 v[104:107], v[206:209], v[182:185], 0
	v_mfma_f32_16x16x32_bf16 v[100:103], v[218:221], v[182:185], 0
	v_mfma_f32_16x16x32_bf16 v[88:91], v[206:209], v[190:193], 0
	v_mfma_f32_16x16x32_bf16 v[84:87], v[218:221], v[190:193], 0
	v_mfma_f32_16x16x32_bf16 v[72:75], v[206:209], v[198:201], 0
	v_mfma_f32_16x16x32_bf16 v[68:71], v[218:221], v[198:201], 0
	v_mfma_f32_16x16x32_bf16 v[120:123], v[214:217], v[170:173], v[120:123]
	v_mfma_f32_16x16x32_bf16 v[116:119], v[222:225], v[170:173], v[116:119]
	v_mfma_f32_16x16x32_bf16 v[104:107], v[214:217], v[186:189], v[104:107]
	v_mfma_f32_16x16x32_bf16 v[100:103], v[222:225], v[186:189], v[100:103]
	v_mfma_f32_16x16x32_bf16 v[88:91], v[214:217], v[194:197], v[88:91]
	v_mfma_f32_16x16x32_bf16 v[84:87], v[222:225], v[194:197], v[84:87]
	v_mfma_f32_16x16x32_bf16 v[72:75], v[214:217], v[202:205], v[72:75]
	v_mfma_f32_16x16x32_bf16 v[68:71], v[222:225], v[202:205], v[68:71]
	s_mov_b32 m0, s44
	v_lshl_add_u64 v[228:229], s[38:39], 0, v[134:135]
	s_barrier
	ds_read_b128 v[166:169], v133 offset:16384
	ds_read_b128 v[170:173], v133 offset:17408
	ds_read_b128 v[182:185], v133 offset:18432
	ds_read_b128 v[186:189], v133 offset:19456
	ds_read_b128 v[190:193], v133 offset:20480
	ds_read_b128 v[194:197], v133 offset:21504
	ds_read_b128 v[198:201], v133 offset:22528
	ds_read_b128 v[202:205], v133 offset:23552
	global_load_lds_dwordx4 v[228:229], off
	s_mov_b32 m0, s45
	v_lshl_add_u64 v[230:231], s[38:39], 0, v[136:137]
	global_load_lds_dwordx4 v[230:231], off
	s_barrier
	s_waitcnt lgkmcnt(0)
	v_mfma_f32_16x16x32_bf16 v[64:67], v[150:153], v[166:169], 0
	v_mfma_f32_16x16x32_bf16 v[60:63], v[158:161], v[166:169], 0
	v_mfma_f32_16x16x32_bf16 v[44:47], v[150:153], v[182:185], 0
	v_mfma_f32_16x16x32_bf16 v[40:43], v[158:161], v[182:185], 0
	v_mfma_f32_16x16x32_bf16 v[28:31], v[150:153], v[190:193], 0
	v_mfma_f32_16x16x32_bf16 v[24:27], v[158:161], v[190:193], 0
	v_mfma_f32_16x16x32_bf16 v[12:15], v[150:153], v[198:201], 0
	v_mfma_f32_16x16x32_bf16 v[8:11], v[158:161], v[198:201], 0
	v_mfma_f32_16x16x32_bf16 v[64:67], v[154:157], v[170:173], v[64:67]
	v_mfma_f32_16x16x32_bf16 v[60:63], v[162:165], v[170:173], v[60:63]
	v_mfma_f32_16x16x32_bf16 v[44:47], v[154:157], v[186:189], v[44:47]
	v_mfma_f32_16x16x32_bf16 v[40:43], v[162:165], v[186:189], v[40:43]
	v_mfma_f32_16x16x32_bf16 v[28:31], v[154:157], v[194:197], v[28:31]
	v_mfma_f32_16x16x32_bf16 v[24:27], v[162:165], v[194:197], v[24:27]
	v_mfma_f32_16x16x32_bf16 v[12:15], v[154:157], v[202:205], v[12:15]
	v_mfma_f32_16x16x32_bf16 v[8:11], v[162:165], v[202:205], v[8:11]
	s_barrier
	s_add_u32 s90, s36, 0x100000
	s_addc_u32 s91, s37, 0
	s_mov_b32 m0, s77
	v_lshl_add_u64 v[150:151], s[90:91], 0, v[134:135]
	global_load_lds_dwordx4 v[150:151], off
	s_mov_b32 m0, s78
	v_lshl_add_u64 v[150:151], s[90:91], 0, v[136:137]
	global_load_lds_dwordx4 v[150:151], off
	s_waitcnt vmcnt(6)
	s_barrier
	v_mfma_f32_16x16x32_bf16 v[52:55], v[206:209], v[166:169], 0
	v_mfma_f32_16x16x32_bf16 v[48:51], v[218:221], v[166:169], 0
	v_mfma_f32_16x16x32_bf16 v[36:39], v[206:209], v[182:185], 0
	v_mfma_f32_16x16x32_bf16 v[32:35], v[218:221], v[182:185], 0
	v_mfma_f32_16x16x32_bf16 v[20:23], v[206:209], v[190:193], 0
	v_mfma_f32_16x16x32_bf16 v[16:19], v[218:221], v[190:193], 0
	v_mfma_f32_16x16x32_bf16 v[4:7], v[206:209], v[198:201], 0
	v_mfma_f32_16x16x32_bf16 v[0:3], v[218:221], v[198:201], 0
	v_mfma_f32_16x16x32_bf16 v[52:55], v[214:217], v[170:173], v[52:55]
	v_mfma_f32_16x16x32_bf16 v[48:51], v[222:225], v[170:173], v[48:51]
	v_mfma_f32_16x16x32_bf16 v[36:39], v[214:217], v[186:189], v[36:39]
	v_mfma_f32_16x16x32_bf16 v[32:35], v[222:225], v[186:189], v[32:35]
	v_mfma_f32_16x16x32_bf16 v[20:23], v[214:217], v[194:197], v[20:23]
	v_mfma_f32_16x16x32_bf16 v[16:19], v[222:225], v[194:197], v[16:19]
	v_mfma_f32_16x16x32_bf16 v[4:7], v[214:217], v[202:205], v[4:7]
	v_mfma_f32_16x16x32_bf16 v[0:3], v[222:225], v[202:205], v[0:3]
	v_add_u32_e32 v56, s79, v139
	s_barrier
	ds_read_b128 v[150:153], v56
	ds_read_b128 v[154:157], v56 offset:1024
	ds_read_b128 v[158:161], v56 offset:2048
	ds_read_b128 v[162:165], v56 offset:3072
	s_add_u32 s38, s38, 0x100000
	s_addc_u32 s39, s39, 0
	s_mov_b32 m0, s46
	v_lshl_add_u64 v[206:207], s[38:39], 0, v[134:135]
	ds_read_b128 v[166:169], v133 offset:32768
	ds_read_b128 v[170:173], v133 offset:33792
	ds_read_b128 v[182:185], v133 offset:34816
	ds_read_b128 v[186:189], v133 offset:35840
	ds_read_b128 v[190:193], v133 offset:36864
	ds_read_b128 v[194:197], v133 offset:37888
	ds_read_b128 v[198:201], v133 offset:38912
	ds_read_b128 v[202:205], v133 offset:39936
	global_load_lds_dwordx4 v[206:207], off
	s_mov_b32 m0, s47
	v_lshl_add_u64 v[206:207], s[38:39], 0, v[136:137]
	global_load_lds_dwordx4 v[206:207], off
	s_waitcnt lgkmcnt(8)
	s_barrier
	s_waitcnt lgkmcnt(0)
	v_mfma_f32_16x16x32_bf16 v[128:131], v[150:153], v[166:169], v[128:131]
	v_mfma_f32_16x16x32_bf16 v[124:127], v[158:161], v[166:169], v[124:127]
	v_mfma_f32_16x16x32_bf16 v[112:115], v[150:153], v[182:185], v[112:115]
	v_mfma_f32_16x16x32_bf16 v[108:111], v[158:161], v[182:185], v[108:111]
	v_mfma_f32_16x16x32_bf16 v[96:99], v[150:153], v[190:193], v[96:99]
	v_mfma_f32_16x16x32_bf16 v[92:95], v[158:161], v[190:193], v[92:95]
	v_mfma_f32_16x16x32_bf16 v[80:83], v[150:153], v[198:201], v[80:83]
	v_mfma_f32_16x16x32_bf16 v[76:79], v[158:161], v[198:201], v[76:79]
	v_mfma_f32_16x16x32_bf16 v[128:131], v[154:157], v[170:173], v[128:131]
	v_mfma_f32_16x16x32_bf16 v[124:127], v[162:165], v[170:173], v[124:127]
	v_mfma_f32_16x16x32_bf16 v[112:115], v[154:157], v[186:189], v[112:115]
	v_mfma_f32_16x16x32_bf16 v[108:111], v[162:165], v[186:189], v[108:111]
	v_mfma_f32_16x16x32_bf16 v[96:99], v[154:157], v[194:197], v[96:99]
	v_mfma_f32_16x16x32_bf16 v[92:95], v[162:165], v[194:197], v[92:95]
	v_mfma_f32_16x16x32_bf16 v[80:83], v[154:157], v[202:205], v[80:83]
	v_mfma_f32_16x16x32_bf16 v[76:79], v[162:165], v[202:205], v[76:79]
	s_barrier
	s_add_i32 s3, 0, 0x1c000
	s_add_i32 s38, s79, s41
	v_add_u32_e32 v56, s3, v139
	v_lshl_add_u64 v[174:175], v[174:175], 0, s[16:17]
	s_mov_b32 m0, s38
	ds_read_b128 v[206:209], v56
	ds_read_b128 v[214:217], v56 offset:1024
	ds_read_b128 v[218:221], v56 offset:2048
	ds_read_b128 v[222:225], v56 offset:3072
	global_load_lds_dwordx4 v[174:175], off
	s_add_i32 m0, s38, 0x2000
	v_lshl_add_u64 v[174:175], v[226:227], 0, s[16:17]
	global_load_lds_dwordx4 v[174:175], off
	s_barrier
	s_waitcnt lgkmcnt(0)
	v_mfma_f32_16x16x32_bf16 v[120:123], v[206:209], v[166:169], v[120:123]
	v_mfma_f32_16x16x32_bf16 v[116:119], v[218:221], v[166:169], v[116:119]
	v_mfma_f32_16x16x32_bf16 v[104:107], v[206:209], v[182:185], v[104:107]
	v_mfma_f32_16x16x32_bf16 v[100:103], v[218:221], v[182:185], v[100:103]
	v_mfma_f32_16x16x32_bf16 v[88:91], v[206:209], v[190:193], v[88:91]
	v_mfma_f32_16x16x32_bf16 v[84:87], v[218:221], v[190:193], v[84:87]
	v_mfma_f32_16x16x32_bf16 v[72:75], v[206:209], v[198:201], v[72:75]
	v_mfma_f32_16x16x32_bf16 v[68:71], v[218:221], v[198:201], v[68:71]
	v_mfma_f32_16x16x32_bf16 v[120:123], v[214:217], v[170:173], v[120:123]
	v_mfma_f32_16x16x32_bf16 v[116:119], v[222:225], v[170:173], v[116:119]
	v_mfma_f32_16x16x32_bf16 v[104:107], v[214:217], v[186:189], v[104:107]
	v_mfma_f32_16x16x32_bf16 v[100:103], v[222:225], v[186:189], v[100:103]
	v_mfma_f32_16x16x32_bf16 v[88:91], v[214:217], v[194:197], v[88:91]
	v_mfma_f32_16x16x32_bf16 v[84:87], v[222:225], v[194:197], v[84:87]
	v_mfma_f32_16x16x32_bf16 v[72:75], v[214:217], v[202:205], v[72:75]
	v_mfma_f32_16x16x32_bf16 v[68:71], v[222:225], v[202:205], v[68:71]
	s_mov_b32 m0, s67
	v_lshl_add_u64 v[174:175], v[228:229], 0, s[16:17]
	s_barrier
	ds_read_b128 v[166:169], v133 offset:49152
	ds_read_b128 v[170:173], v133 offset:50176
	ds_read_b128 v[182:185], v133 offset:51200
	ds_read_b128 v[186:189], v133 offset:52224
	ds_read_b128 v[190:193], v133 offset:53248
	ds_read_b128 v[194:197], v133 offset:54272
	ds_read_b128 v[198:201], v133 offset:55296
	ds_read_b128 v[202:205], v133 offset:56320
	global_load_lds_dwordx4 v[174:175], off
	s_mov_b32 m0, s68
	v_lshl_add_u64 v[174:175], v[230:231], 0, s[16:17]
	global_load_lds_dwordx4 v[174:175], off
	s_barrier
	s_waitcnt lgkmcnt(0)
	v_mfma_f32_16x16x32_bf16 v[64:67], v[150:153], v[166:169], v[64:67]
	v_mfma_f32_16x16x32_bf16 v[60:63], v[158:161], v[166:169], v[60:63]
	v_mfma_f32_16x16x32_bf16 v[44:47], v[150:153], v[182:185], v[44:47]
	v_mfma_f32_16x16x32_bf16 v[40:43], v[158:161], v[182:185], v[40:43]
	v_mfma_f32_16x16x32_bf16 v[28:31], v[150:153], v[190:193], v[28:31]
	v_mfma_f32_16x16x32_bf16 v[24:27], v[158:161], v[190:193], v[24:27]
	v_mfma_f32_16x16x32_bf16 v[12:15], v[150:153], v[198:201], v[12:15]
	v_mfma_f32_16x16x32_bf16 v[8:11], v[158:161], v[198:201], v[8:11]
	v_mfma_f32_16x16x32_bf16 v[64:67], v[154:157], v[170:173], v[64:67]
	v_mfma_f32_16x16x32_bf16 v[60:63], v[162:165], v[170:173], v[60:63]
	v_mfma_f32_16x16x32_bf16 v[44:47], v[154:157], v[186:189], v[44:47]
	v_mfma_f32_16x16x32_bf16 v[40:43], v[162:165], v[186:189], v[40:43]
	v_mfma_f32_16x16x32_bf16 v[28:31], v[154:157], v[194:197], v[28:31]
	v_mfma_f32_16x16x32_bf16 v[24:27], v[162:165], v[194:197], v[24:27]
	v_mfma_f32_16x16x32_bf16 v[12:15], v[154:157], v[202:205], v[12:15]
	v_mfma_f32_16x16x32_bf16 v[8:11], v[162:165], v[202:205], v[8:11]
	s_barrier
	s_add_u32 s36, s36, 0x100080
	s_addc_u32 s37, s37, 0
	s_add_i32 s3, s3, s41
	s_mov_b32 m0, s3
	v_lshl_add_u64 v[150:151], s[36:37], 0, v[134:135]
	global_load_lds_dwordx4 v[150:151], off
	s_add_i32 m0, s3, 0x2000
	v_lshl_add_u64 v[150:151], s[36:37], 0, v[136:137]
	global_load_lds_dwordx4 v[150:151], off
	s_waitcnt vmcnt(6)
	s_barrier
	v_mfma_f32_16x16x32_bf16 v[52:55], v[206:209], v[166:169], v[52:55]
	v_mfma_f32_16x16x32_bf16 v[48:51], v[218:221], v[166:169], v[48:51]
	v_mfma_f32_16x16x32_bf16 v[36:39], v[206:209], v[182:185], v[36:39]
	v_mfma_f32_16x16x32_bf16 v[32:35], v[218:221], v[182:185], v[32:35]
	v_mfma_f32_16x16x32_bf16 v[20:23], v[206:209], v[190:193], v[20:23]
	v_mfma_f32_16x16x32_bf16 v[16:19], v[218:221], v[190:193], v[16:19]
	v_mfma_f32_16x16x32_bf16 v[4:7], v[206:209], v[198:201], v[4:7]
	v_mfma_f32_16x16x32_bf16 v[0:3], v[218:221], v[198:201], v[0:3]
	v_mfma_f32_16x16x32_bf16 v[52:55], v[214:217], v[170:173], v[52:55]
	v_mfma_f32_16x16x32_bf16 v[48:51], v[222:225], v[170:173], v[48:51]
	v_mfma_f32_16x16x32_bf16 v[36:39], v[214:217], v[186:189], v[36:39]
	v_mfma_f32_16x16x32_bf16 v[32:35], v[222:225], v[186:189], v[32:35]
	v_mfma_f32_16x16x32_bf16 v[20:23], v[214:217], v[194:197], v[20:23]
	v_mfma_f32_16x16x32_bf16 v[16:19], v[222:225], v[194:197], v[16:19]
	v_mfma_f32_16x16x32_bf16 v[4:7], v[214:217], v[202:205], v[4:7]
	v_mfma_f32_16x16x32_bf16 v[0:3], v[222:225], v[202:205], v[0:3]
	s_add_u32 s34, s34, 0x100
	s_addc_u32 s35, s35, 0
	s_cmp_ge_u32 s89, s49
	s_cbranch_scc1 .Lrot_exit_out

.LBB0_640:
	s_add_i32 s89, s89, 2
	v_add_u32_e32 v56, s71, v139
	s_add_u32 s3, s22, s34
	ds_read_b128 v[150:153], v56
	ds_read_b128 v[154:157], v56 offset:1024
	ds_read_b128 v[158:161], v56 offset:2048
	ds_read_b128 v[162:165], v56 offset:3072
	s_addc_u32 s36, s23, s35
	s_add_u32 s3, s3, 0x100
	s_addc_u32 s36, s36, 0
	s_add_u32 s90, s83, s34
	s_addc_u32 s37, s84, s35
	s_cmp_eq_u32 s88, s34
	s_cselect_b32 s39, s11, s36
	s_cselect_b32 s38, s85, s3
	s_cselect_b32 s37, s86, s37
	s_cselect_b32 s36, s87, s90
	s_mov_b32 m0, s73
	v_lshl_add_u64 v[174:175], v[58:59], 0, s[34:35]
	ds_read_b128 v[166:169], v133
	ds_read_b128 v[170:173], v133 offset:1024
	ds_read_b128 v[182:185], v133 offset:2048
	ds_read_b128 v[186:189], v133 offset:3072
	ds_read_b128 v[190:193], v133 offset:4096
	ds_read_b128 v[194:197], v133 offset:5120
	ds_read_b128 v[198:201], v133 offset:6144
	ds_read_b128 v[202:205], v133 offset:7168
	global_load_lds_dwordx4 v[174:175], off
	s_mov_b32 m0, s74
	v_lshl_add_u64 v[174:175], v[146:147], 0, s[34:35]
	global_load_lds_dwordx4 v[174:175], off
	s_waitcnt lgkmcnt(8)
	s_barrier
	s_waitcnt lgkmcnt(0)
	v_mfma_f32_16x16x32_bf16 v[128:131], v[150:153], v[166:169], v[128:131]
	v_mfma_f32_16x16x32_bf16 v[124:127], v[158:161], v[166:169], v[124:127]
	v_mfma_f32_16x16x32_bf16 v[112:115], v[150:153], v[182:185], v[112:115]
	v_mfma_f32_16x16x32_bf16 v[108:111], v[158:161], v[182:185], v[108:111]
	v_mfma_f32_16x16x32_bf16 v[96:99], v[150:153], v[190:193], v[96:99]
	v_mfma_f32_16x16x32_bf16 v[92:95], v[158:161], v[190:193], v[92:95]
	v_mfma_f32_16x16x32_bf16 v[80:83], v[150:153], v[198:201], v[80:83]
	v_mfma_f32_16x16x32_bf16 v[76:79], v[158:161], v[198:201], v[76:79]
	v_mfma_f32_16x16x32_bf16 v[128:131], v[154:157], v[170:173], v[128:131]
	v_mfma_f32_16x16x32_bf16 v[124:127], v[162:165], v[170:173], v[124:127]
	v_mfma_f32_16x16x32_bf16 v[112:115], v[154:157], v[186:189], v[112:115]
	v_mfma_f32_16x16x32_bf16 v[108:111], v[162:165], v[186:189], v[108:111]
	v_mfma_f32_16x16x32_bf16 v[96:99], v[154:157], v[194:197], v[96:99]
	v_mfma_f32_16x16x32_bf16 v[92:95], v[162:165], v[194:197], v[92:95]
	v_mfma_f32_16x16x32_bf16 v[80:83], v[154:157], v[202:205], v[80:83]
	v_mfma_f32_16x16x32_bf16 v[76:79], v[162:165], v[202:205], v[76:79]
	s_barrier
	s_mov_b32 m0, s75
	v_add_u32_e32 v56, s72, v139
	v_lshl_add_u64 v[174:175], s[36:37], 0, v[134:135]
	ds_read_b128 v[206:209], v56
	ds_read_b128 v[214:217], v56 offset:1024
	ds_read_b128 v[218:221], v56 offset:2048
	ds_read_b128 v[222:225], v56 offset:3072
	global_load_lds_dwordx4 v[174:175], off
	s_mov_b32 m0, s76
	v_lshl_add_u64 v[226:227], s[36:37], 0, v[136:137]
	global_load_lds_dwordx4 v[226:227], off
	s_barrier
	s_waitcnt lgkmcnt(0)
	v_mfma_f32_16x16x32_bf16 v[120:123], v[206:209], v[166:169], v[120:123]
	v_mfma_f32_16x16x32_bf16 v[116:119], v[218:221], v[166:169], v[116:119]
	v_mfma_f32_16x16x32_bf16 v[104:107], v[206:209], v[182:185], v[104:107]
	v_mfma_f32_16x16x32_bf16 v[100:103], v[218:221], v[182:185], v[100:103]
	v_mfma_f32_16x16x32_bf16 v[88:91], v[206:209], v[190:193], v[88:91]
	v_mfma_f32_16x16x32_bf16 v[84:87], v[218:221], v[190:193], v[84:87]
	v_mfma_f32_16x16x32_bf16 v[72:75], v[206:209], v[198:201], v[72:75]
	v_mfma_f32_16x16x32_bf16 v[68:71], v[218:221], v[198:201], v[68:71]
	v_mfma_f32_16x16x32_bf16 v[120:123], v[214:217], v[170:173], v[120:123]
	v_mfma_f32_16x16x32_bf16 v[116:119], v[222:225], v[170:173], v[116:119]
	v_mfma_f32_16x16x32_bf16 v[104:107], v[214:217], v[186:189], v[104:107]
	v_mfma_f32_16x16x32_bf16 v[100:103], v[222:225], v[186:189], v[100:103]
	v_mfma_f32_16x16x32_bf16 v[88:91], v[214:217], v[194:197], v[88:91]
	v_mfma_f32_16x16x32_bf16 v[84:87], v[222:225], v[194:197], v[84:87]
	v_mfma_f32_16x16x32_bf16 v[72:75], v[214:217], v[202:205], v[72:75]
	v_mfma_f32_16x16x32_bf16 v[68:71], v[222:225], v[202:205], v[68:71]
	s_mov_b32 m0, s44
	v_lshl_add_u64 v[228:229], s[38:39], 0, v[134:135]
	s_barrier
	ds_read_b128 v[166:169], v133 offset:16384
	ds_read_b128 v[170:173], v133 offset:17408
	ds_read_b128 v[182:185], v133 offset:18432
	ds_read_b128 v[186:189], v133 offset:19456
	ds_read_b128 v[190:193], v133 offset:20480
	ds_read_b128 v[194:197], v133 offset:21504
	ds_read_b128 v[198:201], v133 offset:22528
	ds_read_b128 v[202:205], v133 offset:23552
	global_load_lds_dwordx4 v[228:229], off
	s_mov_b32 m0, s45
	v_lshl_add_u64 v[230:231], s[38:39], 0, v[136:137]
	global_load_lds_dwordx4 v[230:231], off
	s_barrier
	s_waitcnt lgkmcnt(0)
	v_mfma_f32_16x16x32_bf16 v[64:67], v[150:153], v[166:169], v[64:67]
	v_mfma_f32_16x16x32_bf16 v[60:63], v[158:161], v[166:169], v[60:63]
	v_mfma_f32_16x16x32_bf16 v[44:47], v[150:153], v[182:185], v[44:47]
	v_mfma_f32_16x16x32_bf16 v[40:43], v[158:161], v[182:185], v[40:43]
	v_mfma_f32_16x16x32_bf16 v[28:31], v[150:153], v[190:193], v[28:31]
	v_mfma_f32_16x16x32_bf16 v[24:27], v[158:161], v[190:193], v[24:27]
	v_mfma_f32_16x16x32_bf16 v[12:15], v[150:153], v[198:201], v[12:15]
	v_mfma_f32_16x16x32_bf16 v[8:11], v[158:161], v[198:201], v[8:11]
	v_mfma_f32_16x16x32_bf16 v[64:67], v[154:157], v[170:173], v[64:67]
	v_mfma_f32_16x16x32_bf16 v[60:63], v[162:165], v[170:173], v[60:63]
	v_mfma_f32_16x16x32_bf16 v[44:47], v[154:157], v[186:189], v[44:47]
	v_mfma_f32_16x16x32_bf16 v[40:43], v[162:165], v[186:189], v[40:43]
	v_mfma_f32_16x16x32_bf16 v[28:31], v[154:157], v[194:197], v[28:31]
	v_mfma_f32_16x16x32_bf16 v[24:27], v[162:165], v[194:197], v[24:27]
	v_mfma_f32_16x16x32_bf16 v[12:15], v[154:157], v[202:205], v[12:15]
	v_mfma_f32_16x16x32_bf16 v[8:11], v[162:165], v[202:205], v[8:11]
	s_barrier
	s_add_u32 s90, s36, 0x100000
	s_addc_u32 s91, s37, 0
	s_mov_b32 m0, s77
	v_lshl_add_u64 v[150:151], s[90:91], 0, v[134:135]
	global_load_lds_dwordx4 v[150:151], off
	s_mov_b32 m0, s78
	v_lshl_add_u64 v[150:151], s[90:91], 0, v[136:137]
	global_load_lds_dwordx4 v[150:151], off
	s_waitcnt vmcnt(6)
	s_barrier
	v_mfma_f32_16x16x32_bf16 v[52:55], v[206:209], v[166:169], v[52:55]
	v_mfma_f32_16x16x32_bf16 v[48:51], v[218:221], v[166:169], v[48:51]
	v_mfma_f32_16x16x32_bf16 v[36:39], v[206:209], v[182:185], v[36:39]
	v_mfma_f32_16x16x32_bf16 v[32:35], v[218:221], v[182:185], v[32:35]
	v_mfma_f32_16x16x32_bf16 v[20:23], v[206:209], v[190:193], v[20:23]
	v_mfma_f32_16x16x32_bf16 v[16:19], v[218:221], v[190:193], v[16:19]
	v_mfma_f32_16x16x32_bf16 v[4:7], v[206:209], v[198:201], v[4:7]
	v_mfma_f32_16x16x32_bf16 v[0:3], v[218:221], v[198:201], v[0:3]
	v_mfma_f32_16x16x32_bf16 v[52:55], v[214:217], v[170:173], v[52:55]
	v_mfma_f32_16x16x32_bf16 v[48:51], v[222:225], v[170:173], v[48:51]
	v_mfma_f32_16x16x32_bf16 v[36:39], v[214:217], v[186:189], v[36:39]
	v_mfma_f32_16x16x32_bf16 v[32:35], v[222:225], v[186:189], v[32:35]
	v_mfma_f32_16x16x32_bf16 v[20:23], v[214:217], v[194:197], v[20:23]
	v_mfma_f32_16x16x32_bf16 v[16:19], v[222:225], v[194:197], v[16:19]
	v_mfma_f32_16x16x32_bf16 v[4:7], v[214:217], v[202:205], v[4:7]
	v_mfma_f32_16x16x32_bf16 v[0:3], v[222:225], v[202:205], v[0:3]
	v_add_u32_e32 v56, s79, v139
	s_barrier
	ds_read_b128 v[150:153], v56
	ds_read_b128 v[154:157], v56 offset:1024
	ds_read_b128 v[158:161], v56 offset:2048
	ds_read_b128 v[162:165], v56 offset:3072
	s_add_u32 s38, s38, 0x100000
	s_addc_u32 s39, s39, 0
	s_mov_b32 m0, s46
	v_lshl_add_u64 v[206:207], s[38:39], 0, v[134:135]
	ds_read_b128 v[166:169], v133 offset:32768
	ds_read_b128 v[170:173], v133 offset:33792
	ds_read_b128 v[182:185], v133 offset:34816
	ds_read_b128 v[186:189], v133 offset:35840
	ds_read_b128 v[190:193], v133 offset:36864
	ds_read_b128 v[194:197], v133 offset:37888
	ds_read_b128 v[198:201], v133 offset:38912
	ds_read_b128 v[202:205], v133 offset:39936
	global_load_lds_dwordx4 v[206:207], off
	s_mov_b32 m0, s47
	v_lshl_add_u64 v[206:207], s[38:39], 0, v[136:137]
	global_load_lds_dwordx4 v[206:207], off
	s_waitcnt lgkmcnt(8)
	s_barrier
	s_waitcnt lgkmcnt(0)
	v_mfma_f32_16x16x32_bf16 v[128:131], v[150:153], v[166:169], v[128:131]
	v_mfma_f32_16x16x32_bf16 v[124:127], v[158:161], v[166:169], v[124:127]
	v_mfma_f32_16x16x32_bf16 v[112:115], v[150:153], v[182:185], v[112:115]
	v_mfma_f32_16x16x32_bf16 v[108:111], v[158:161], v[182:185], v[108:111]
	v_mfma_f32_16x16x32_bf16 v[96:99], v[150:153], v[190:193], v[96:99]
	v_mfma_f32_16x16x32_bf16 v[92:95], v[158:161], v[190:193], v[92:95]
	v_mfma_f32_16x16x32_bf16 v[80:83], v[150:153], v[198:201], v[80:83]
	v_mfma_f32_16x16x32_bf16 v[76:79], v[158:161], v[198:201], v[76:79]
	v_mfma_f32_16x16x32_bf16 v[128:131], v[154:157], v[170:173], v[128:131]
	v_mfma_f32_16x16x32_bf16 v[124:127], v[162:165], v[170:173], v[124:127]
	v_mfma_f32_16x16x32_bf16 v[112:115], v[154:157], v[186:189], v[112:115]
	v_mfma_f32_16x16x32_bf16 v[108:111], v[162:165], v[186:189], v[108:111]
	v_mfma_f32_16x16x32_bf16 v[96:99], v[154:157], v[194:197], v[96:99]
	v_mfma_f32_16x16x32_bf16 v[92:95], v[162:165], v[194:197], v[92:95]
	v_mfma_f32_16x16x32_bf16 v[80:83], v[154:157], v[202:205], v[80:83]
	v_mfma_f32_16x16x32_bf16 v[76:79], v[162:165], v[202:205], v[76:79]
	s_barrier
	s_add_i32 s3, 0, 0x1c000
	s_add_i32 s38, s79, s41
	v_add_u32_e32 v56, s3, v139
	v_lshl_add_u64 v[174:175], v[174:175], 0, s[16:17]
	s_mov_b32 m0, s38
	ds_read_b128 v[206:209], v56
	ds_read_b128 v[214:217], v56 offset:1024
	ds_read_b128 v[218:221], v56 offset:2048
	ds_read_b128 v[222:225], v56 offset:3072
	global_load_lds_dwordx4 v[174:175], off
	s_add_i32 m0, s38, 0x2000
	v_lshl_add_u64 v[174:175], v[226:227], 0, s[16:17]
	global_load_lds_dwordx4 v[174:175], off
	s_barrier
	s_waitcnt lgkmcnt(0)
	v_mfma_f32_16x16x32_bf16 v[120:123], v[206:209], v[166:169], v[120:123]
	v_mfma_f32_16x16x32_bf16 v[116:119], v[218:221], v[166:169], v[116:119]
	v_mfma_f32_16x16x32_bf16 v[104:107], v[206:209], v[182:185], v[104:107]
	v_mfma_f32_16x16x32_bf16 v[100:103], v[218:221], v[182:185], v[100:103]
	v_mfma_f32_16x16x32_bf16 v[88:91], v[206:209], v[190:193], v[88:91]
	v_mfma_f32_16x16x32_bf16 v[84:87], v[218:221], v[190:193], v[84:87]
	v_mfma_f32_16x16x32_bf16 v[72:75], v[206:209], v[198:201], v[72:75]
	v_mfma_f32_16x16x32_bf16 v[68:71], v[218:221], v[198:201], v[68:71]
	v_mfma_f32_16x16x32_bf16 v[120:123], v[214:217], v[170:173], v[120:123]
	v_mfma_f32_16x16x32_bf16 v[116:119], v[222:225], v[170:173], v[116:119]
	v_mfma_f32_16x16x32_bf16 v[104:107], v[214:217], v[186:189], v[104:107]
	v_mfma_f32_16x16x32_bf16 v[100:103], v[222:225], v[186:189], v[100:103]
	v_mfma_f32_16x16x32_bf16 v[88:91], v[214:217], v[194:197], v[88:91]
	v_mfma_f32_16x16x32_bf16 v[84:87], v[222:225], v[194:197], v[84:87]
	v_mfma_f32_16x16x32_bf16 v[72:75], v[214:217], v[202:205], v[72:75]
	v_mfma_f32_16x16x32_bf16 v[68:71], v[222:225], v[202:205], v[68:71]
	s_mov_b32 m0, s67
	v_lshl_add_u64 v[174:175], v[228:229], 0, s[16:17]
	s_barrier
	ds_read_b128 v[166:169], v133 offset:49152
	ds_read_b128 v[170:173], v133 offset:50176
	ds_read_b128 v[182:185], v133 offset:51200
	ds_read_b128 v[186:189], v133 offset:52224
	ds_read_b128 v[190:193], v133 offset:53248
	ds_read_b128 v[194:197], v133 offset:54272
	ds_read_b128 v[198:201], v133 offset:55296
	ds_read_b128 v[202:205], v133 offset:56320
	global_load_lds_dwordx4 v[174:175], off
	s_mov_b32 m0, s68
	v_lshl_add_u64 v[174:175], v[230:231], 0, s[16:17]
	global_load_lds_dwordx4 v[174:175], off
	s_barrier
	s_waitcnt lgkmcnt(0)
	v_mfma_f32_16x16x32_bf16 v[64:67], v[150:153], v[166:169], v[64:67]
	v_mfma_f32_16x16x32_bf16 v[60:63], v[158:161], v[166:169], v[60:63]
	v_mfma_f32_16x16x32_bf16 v[44:47], v[150:153], v[182:185], v[44:47]
	v_mfma_f32_16x16x32_bf16 v[40:43], v[158:161], v[182:185], v[40:43]
	v_mfma_f32_16x16x32_bf16 v[28:31], v[150:153], v[190:193], v[28:31]
	v_mfma_f32_16x16x32_bf16 v[24:27], v[158:161], v[190:193], v[24:27]
	v_mfma_f32_16x16x32_bf16 v[12:15], v[150:153], v[198:201], v[12:15]
	v_mfma_f32_16x16x32_bf16 v[8:11], v[158:161], v[198:201], v[8:11]
	v_mfma_f32_16x16x32_bf16 v[64:67], v[154:157], v[170:173], v[64:67]
	v_mfma_f32_16x16x32_bf16 v[60:63], v[162:165], v[170:173], v[60:63]
	v_mfma_f32_16x16x32_bf16 v[44:47], v[154:157], v[186:189], v[44:47]
	v_mfma_f32_16x16x32_bf16 v[40:43], v[162:165], v[186:189], v[40:43]
	v_mfma_f32_16x16x32_bf16 v[28:31], v[154:157], v[194:197], v[28:31]
	v_mfma_f32_16x16x32_bf16 v[24:27], v[162:165], v[194:197], v[24:27]
	v_mfma_f32_16x16x32_bf16 v[12:15], v[154:157], v[202:205], v[12:15]
	v_mfma_f32_16x16x32_bf16 v[8:11], v[162:165], v[202:205], v[8:11]
	s_barrier
	s_add_u32 s36, s36, 0x100080
	s_addc_u32 s37, s37, 0
	s_add_i32 s3, s3, s41
	s_mov_b32 m0, s3
	v_lshl_add_u64 v[150:151], s[36:37], 0, v[134:135]
	global_load_lds_dwordx4 v[150:151], off
	s_add_i32 m0, s3, 0x2000
	v_lshl_add_u64 v[150:151], s[36:37], 0, v[136:137]
	global_load_lds_dwordx4 v[150:151], off
	s_waitcnt vmcnt(6)
	s_barrier
	v_mfma_f32_16x16x32_bf16 v[52:55], v[206:209], v[166:169], v[52:55]
	v_mfma_f32_16x16x32_bf16 v[48:51], v[218:221], v[166:169], v[48:51]
	v_mfma_f32_16x16x32_bf16 v[36:39], v[206:209], v[182:185], v[36:39]
	v_mfma_f32_16x16x32_bf16 v[32:35], v[218:221], v[182:185], v[32:35]
	v_mfma_f32_16x16x32_bf16 v[20:23], v[206:209], v[190:193], v[20:23]
	v_mfma_f32_16x16x32_bf16 v[16:19], v[218:221], v[190:193], v[16:19]
	v_mfma_f32_16x16x32_bf16 v[4:7], v[206:209], v[198:201], v[4:7]
	v_mfma_f32_16x16x32_bf16 v[0:3], v[218:221], v[198:201], v[0:3]
	v_mfma_f32_16x16x32_bf16 v[52:55], v[214:217], v[170:173], v[52:55]
	v_mfma_f32_16x16x32_bf16 v[48:51], v[222:225], v[170:173], v[48:51]
	v_mfma_f32_16x16x32_bf16 v[36:39], v[214:217], v[186:189], v[36:39]
	v_mfma_f32_16x16x32_bf16 v[32:35], v[222:225], v[186:189], v[32:35]
	v_mfma_f32_16x16x32_bf16 v[20:23], v[214:217], v[194:197], v[20:23]
	v_mfma_f32_16x16x32_bf16 v[16:19], v[222:225], v[194:197], v[16:19]
	v_mfma_f32_16x16x32_bf16 v[4:7], v[214:217], v[202:205], v[4:7]
	v_mfma_f32_16x16x32_bf16 v[0:3], v[222:225], v[202:205], v[0:3]
	s_add_u32 s34, s34, 0x100
	s_addc_u32 s35, s35, 0
	s_cmp_ge_u32 s89, s49
	s_cbranch_scc0 .Lrot_out
